# norm phases 9/12/16/19: wave reduction via permlane32/16 swap + DPP row_ror/quad_perm instead of six ds_bpermute LDS round trips
# speedup vs baseline: 1.0021x; 1.0021x over previous
; __device__ __forceinline__ u16 f2bf(float x) { unsigned u = __float_as_uint(x); u += 0x7fffu + ((u >> 16) & 1u); return (u16)(u >> 16); }
; __device__ __forceinline__ size_t a_off(int row, int col, int nks) { return ((size_t)((row >> 8) * nks + (col >> 5)) << 13) + ((row & 255) << 5) + swzc(row, col & 31); }
; template <int MODE>
; __device__ __forceinline__ void norm_phase(const Params& p, const float* src, const float* w, const float* modl, int sh_off, int sc_off,
;                            char* smem, int bid, int nblk) {
;     ...
;     float ss = 0.f;
; #pragma unroll
;     for (int i = 0; i < 4; ++i) ss += v[i][0] * v[i][0] + v[i][1] * v[i][1] + v[i][2] * v[i][2] + v[i][3] * v[i][3];
; #pragma unroll
;     for (int o = 32; o >= 1; o >>= 1) ss += __shfl_xor(ss, o);
;     const float rstd = rsqrtf(ss * (1.f / 1024.f) + 1e-6f);
;     const int b = row >> 13;
;     float dots[8];
;     if (MODE == 1) { for (int j = 0; j < 8; ++j) dots[j] = 0.f; }
; #pragma unroll
;     for (int i = 0; i < 4; ++i) {
;       const int c0 = i * 256 + lane * 4;
;       f32x4 ww = *(const f32x4*)(w + c0);
;       f32x4 y;
;       if (MODE == 2) {
; #pragma unroll
;         for (int e = 0; e < 4; ++e) y[e] = v[i][e] * rstd * ww[e];
;         *(f32x4*)(p.out + (size_t)row * 1024 + c0) = y;
;       } else {
;         f32x4 sc = *(const f32x4*)(modl + (size_t)b * 6144 + sc_off + c0);
;         f32x4 sh = *(const f32x4*)(modl + (size_t)b * 6144 + sh_off + c0);
; #pragma unroll
;         for (int e = 0; e < 4; ++e) y[e] = v[i][e] * rstd * ww[e] * (1.f + sc[e]) + sh[e];
;         uint2 pk; pk.x = (unsigned)f2bf(y[0]) | ((unsigned)f2bf(y[1]) << 16); pk.y = (unsigned)f2bf(y[2]) | ((unsigned)f2bf(y[3]) << 16);
;         *(uint2*)(hn + a_off(row, c0, 32)) = pk;
.LBB0_1428:
	s_or_b64 exec, exec, s[0:1]
	v_ashrrev_i32_e32 v34, 13, v33
	v_mul_i32_i24_e32 v60, 0x1800, v34
	v_readlane_b32 s0, v244, 23
	v_ashrrev_i32_e32 v61, 31, v60
	v_readlane_b32 s1, v244, 24
	global_load_dwordx4 v[82:85], v[38:39], off
	s_waitcnt vmcnt(0)
	v_pk_mul_f32 v[96:97], v[28:29], v[28:29]
	v_lshl_add_u64 v[62:63], v[60:61], 2, s[0:1]
	v_lshl_add_u64 v[60:61], v[62:63], 0, s[12:13]
	v_lshl_add_u64 v[86:87], v[60:61], 0, v[44:45]
	v_lshl_add_u64 v[62:63], v[62:63], 0, s[14:15]
	global_load_dwordx4 v[86:89], v[86:87], off
	v_lshl_add_u64 v[90:91], v[62:63], 0, v[44:45]
	global_load_dwordx4 v[90:93], v[90:91], off
	v_pk_mul_f32 v[98:99], v[24:25], v[24:25]
	v_pk_mul_f32 v[64:65], v[30:31], v[30:31]
	v_pk_mul_f32 v[94:95], v[26:27], v[26:27]
	v_mov_b32_e32 v100, v96
	v_mov_b32_e32 v101, v98
	v_mov_b32_e32 v98, v97
	v_pk_add_f32 v[96:97], v[100:101], v[98:99]
	v_mov_b32_e32 v98, v64
	v_mov_b32_e32 v99, v94
	v_pk_add_f32 v[96:97], v[98:99], v[96:97]
	v_mov_b32_e32 v94, v65
	v_pk_add_f32 v[64:65], v[94:95], v[96:97]
	v_mov_b32_e32 v96, v17
	v_mov_b32_e32 v97, v21
	v_mov_b32_e32 v94, v16
	v_mov_b32_e32 v95, v20
	v_pk_mul_f32 v[96:97], v[96:97], v[96:97]
	v_add_f32_e32 v34, v64, v65
	v_pk_fma_f32 v[94:95], v[94:95], v[94:95], v[96:97]
	v_mov_b32_e32 v96, v18
	v_mov_b32_e32 v97, v22
	v_pk_fma_f32 v[94:95], v[96:97], v[96:97], v[94:95]
	v_mov_b32_e32 v96, v19
	v_mov_b32_e32 v97, v23
	v_pk_fma_f32 v[94:95], v[96:97], v[96:97], v[94:95]
	v_and_b32_e32 v55, 24, v77
	v_add_f32_e32 v34, v95, v34
	v_add_f32_e32 v34, v94, v34
	s_nop 1
	v_mov_b32_e32 v43, v34
	s_nop 1
	v_permlane32_swap_b32_e32 v34, v43
	v_mov_b32_e32 v95, v30
	v_mov_b32_e32 v30, v29
	v_and_b32_e32 v51, 0x1fe0, v78
	v_sub_u32_e32 v55, 0, v55
	s_waitcnt lgkmcnt(0)
	v_add_f32_e32 v34, v34, v43
	s_nop 1
	v_mov_b32_e32 v43, v34
	s_nop 1
	v_permlane16_swap_b32_e32 v34, v43
	v_mov_b32_e32 v94, v28
	v_ashrrev_i32_e32 v47, 3, v33
	v_and_b32_e32 v47, 0xffffffe0, v47
	v_or_b32_e32 v28, v47, v72
	s_waitcnt lgkmcnt(0)
	v_add_f32_e32 v34, v34, v43
	s_nop 1
	v_mov_b32_dpp v43, v34 row_ror:8 row_mask:0xf bank_mask:0xf
	v_mov_b32_e32 v65, v35
	s_waitcnt lgkmcnt(0)
	v_add_f32_e32 v34, v34, v43
	s_nop 1
	v_mov_b32_dpp v43, v34 row_ror:4 row_mask:0xf bank_mask:0xf
	s_waitcnt lgkmcnt(0)
	v_add_f32_e32 v29, v34, v43
	s_nop 1
	v_mov_b32_dpp v43, v29 quad_perm:[2,3,0,1] row_mask:0xf bank_mask:0xf
	v_lshlrev_b32_e32 v34, 1, v51
	v_xor_b32_e32 v51, v32, v55
	v_and_or_b32 v51, v51, 24, v73
	v_lshlrev_b32_e32 v64, 1, v51
	s_waitcnt lgkmcnt(0)
	v_add_f32_e32 v43, v29, v43
	s_nop 1
	v_mov_b32_dpp v55, v43 quad_perm:[1,0,3,2] row_mask:0xf bank_mask:0xf
	v_ashrrev_i32_e32 v29, 31, v28
	v_lshlrev_b64 v[28:29], 14, v[28:29]
	v_lshl_add_u64 v[28:29], s[62:63], 0, v[28:29]
	v_lshl_add_u64 v[28:29], v[28:29], 0, v[34:35]
	s_waitcnt lgkmcnt(0)
	v_add_f32_e32 v43, v43, v55
	v_fmamk_f32 v43, v43, 0x3a800000, v79
	v_mul_f32_e32 v51, 0x4b800000, v43
	v_cmp_gt_f32_e64 s[0:1], s18, v43
	v_lshl_add_u64 v[28:29], v[28:29], 0, v[64:65]
	v_mov_b32_e32 v98, v82
	v_cndmask_b32_e64 v43, v43, v51, s[0:1]
	v_rsq_f32_e32 v43, v43
	v_mov_b32_e32 v99, v84
	v_mov_b32_e32 v84, v83
	v_mul_f32_e32 v51, 0x45800000, v43
	v_cndmask_b32_e64 v96, v43, v51, s[0:1]
	v_pk_mul_f32 v[94:95], v[94:95], v[96:97] op_sel_hi:[1,0]
	v_pk_mul_f32 v[30:31], v[30:31], v[96:97] op_sel_hi:[1,0]
	v_pk_mul_f32 v[82:83], v[98:99], v[94:95]
	s_waitcnt vmcnt(1)
	v_mov_b32_e32 v95, v88
	v_mov_b32_e32 v88, v87
	v_mov_b32_e32 v94, v86
	s_waitcnt vmcnt(0)
	v_mov_b32_e32 v99, v92
	v_pk_mul_f32 v[30:31], v[84:85], v[30:31]
	v_pk_add_f32 v[84:85], v[88:89], 1.0 op_sel_hi:[1,0]
	v_mov_b32_e32 v92, v91
	v_mov_b32_e32 v98, v90
	v_pk_add_f32 v[94:95], v[94:95], 1.0 op_sel_hi:[1,0]
	v_pk_fma_f32 v[30:31], v[84:85], v[30:31], v[92:93]
	v_pk_fma_f32 v[82:83], v[94:95], v[82:83], v[98:99]
	v_and_b32_sdwa v55, v31, v80 dst_sel:DWORD dst_unused:UNUSED_PAD src0_sel:WORD_1 src1_sel:DWORD
	v_and_b32_sdwa v59, v30, v80 dst_sel:DWORD dst_unused:UNUSED_PAD src0_sel:WORD_1 src1_sel:DWORD
	v_and_b32_sdwa v43, v83, v80 dst_sel:DWORD dst_unused:UNUSED_PAD src0_sel:WORD_1 src1_sel:DWORD
	v_and_b32_sdwa v51, v82, v80 dst_sel:DWORD dst_unused:UNUSED_PAD src0_sel:WORD_1 src1_sel:DWORD
	v_add3_u32 v31, v31, v55, s19
	v_add3_u32 v30, v30, v59, s19
	v_add3_u32 v51, v82, v51, s19
	v_add3_u32 v43, v83, v43, s19
	v_and_b32_e32 v31, 0xffff0000, v31
	v_and_b32_e32 v30, 0xffff0000, v30
	v_or_b32_sdwa v31, v31, v43 dst_sel:DWORD dst_unused:UNUSED_PAD src0_sel:DWORD src1_sel:WORD_1
	v_or_b32_sdwa v30, v30, v51 dst_sel:DWORD dst_unused:UNUSED_PAD src0_sel:DWORD src1_sel:WORD_1
	v_mov_b32_e32 v250, v28
	v_mov_b32_e32 v251, v29
	v_mov_b32_e32 v252, v30
	v_mov_b32_e32 v253, v31
	v_lshl_add_u64 v[82:83], v[60:61], 0, v[48:49]
	global_load_dwordx4 v[28:31], v[38:39], off offset:1024
	v_lshl_add_u64 v[86:87], v[62:63], 0, v[48:49]
	global_load_dwordx4 v[82:85], v[82:83], off
	v_mov_b32_e32 v91, v26
	global_load_dwordx4 v[86:89], v[86:87], off
	global_store_dwordx2 v[250:251], v[252:253], off
	v_mov_b32_e32 v26, v25
	v_mov_b32_e32 v90, v24
	v_pk_mul_f32 v[26:27], v[26:27], v[96:97] op_sel_hi:[1,0]
	v_or_b32_e32 v24, v47, v74
	v_pk_mul_f32 v[90:91], v[90:91], v[96:97] op_sel_hi:[1,0]
	v_ashrrev_i32_e32 v25, 31, v24
	v_lshlrev_b64 v[24:25], 14, v[24:25]
	v_lshl_add_u64 v[24:25], s[62:63], 0, v[24:25]
	v_lshl_add_u64 v[24:25], v[24:25], 0, v[34:35]
	v_lshl_add_u64 v[24:25], v[24:25], 0, v[64:65]
	s_waitcnt vmcnt(3)
	v_mov_b32_e32 v93, v30
	v_mov_b32_e32 v30, v29
	s_waitcnt vmcnt(2)
	v_mov_b32_e32 v95, v84
	v_mov_b32_e32 v84, v83
	v_mov_b32_e32 v92, v28
	v_mov_b32_e32 v94, v82
	s_waitcnt vmcnt(1)
; __device__ __forceinline__ u16 f2bf(float x) { unsigned u = __float_as_uint(x); u += 0x7fffu + ((u >> 16) & 1u); return (u16)(u >> 16); }
; __device__ __forceinline__ size_t a_off(int row, int col, int nks) { return ((size_t)((row >> 8) * nks + (col >> 5)) << 13) + ((row & 255) << 5) + swzc(row, col & 31); }
; template <int MODE>
; __device__ __forceinline__ void norm_phase(const Params& p, const float* src, const float* w, const float* modl, int sh_off, int sc_off,
;                            char* smem, int bid, int nblk) {
;     ...
;       f32x4 ww = *(const f32x4*)(w + c0);
;       f32x4 y;
;       if (MODE == 2) {
; #pragma unroll
;         for (int e = 0; e < 4; ++e) y[e] = v[i][e] * rstd * ww[e];
;         *(f32x4*)(p.out + (size_t)row * 1024 + c0) = y;
;       } else {
;         f32x4 sc = *(const f32x4*)(modl + (size_t)b * 6144 + sc_off + c0);
;         f32x4 sh = *(const f32x4*)(modl + (size_t)b * 6144 + sh_off + c0);
; #pragma unroll
;         for (int e = 0; e < 4; ++e) y[e] = v[i][e] * rstd * ww[e] * (1.f + sc[e]) + sh[e];
;         uint2 pk; pk.x = (unsigned)f2bf(y[0]) | ((unsigned)f2bf(y[1]) << 16); pk.y = (unsigned)f2bf(y[2]) | ((unsigned)f2bf(y[3]) << 16);
;         *(uint2*)(hn + a_off(row, c0, 32)) = pk;
	v_mov_b32_e32 v99, v88
	v_mov_b32_e32 v88, v87
	v_pk_mul_f32 v[26:27], v[30:31], v[26:27]
	v_pk_add_f32 v[30:31], v[84:85], 1.0 op_sel_hi:[1,0]
	v_mov_b32_e32 v98, v86
	v_pk_mul_f32 v[28:29], v[92:93], v[90:91]
	v_pk_add_f32 v[82:83], v[94:95], 1.0 op_sel_hi:[1,0]
	v_pk_fma_f32 v[26:27], v[30:31], v[26:27], v[88:89]
	v_pk_fma_f32 v[28:29], v[82:83], v[28:29], v[98:99]
	v_and_b32_sdwa v43, v27, v80 dst_sel:DWORD dst_unused:UNUSED_PAD src0_sel:WORD_1 src1_sel:DWORD
	v_and_b32_sdwa v51, v26, v80 dst_sel:DWORD dst_unused:UNUSED_PAD src0_sel:WORD_1 src1_sel:DWORD
	v_and_b32_sdwa v30, v29, v80 dst_sel:DWORD dst_unused:UNUSED_PAD src0_sel:WORD_1 src1_sel:DWORD
	v_and_b32_sdwa v31, v28, v80 dst_sel:DWORD dst_unused:UNUSED_PAD src0_sel:WORD_1 src1_sel:DWORD
	v_add3_u32 v27, v27, v43, s19
	v_add3_u32 v26, v26, v51, s19
	v_add3_u32 v28, v28, v31, s19
	v_add3_u32 v29, v29, v30, s19
	v_and_b32_e32 v27, 0xffff0000, v27
	v_and_b32_e32 v26, 0xffff0000, v26
	v_or_b32_sdwa v27, v27, v29 dst_sel:DWORD dst_unused:UNUSED_PAD src0_sel:DWORD src1_sel:WORD_1
	v_or_b32_sdwa v26, v26, v28 dst_sel:DWORD dst_unused:UNUSED_PAD src0_sel:DWORD src1_sel:WORD_1
	v_mov_b32_e32 v250, v24
	v_mov_b32_e32 v251, v25
	v_mov_b32_e32 v252, v26
	v_mov_b32_e32 v253, v27
	v_lshl_add_u64 v[28:29], v[60:61], 0, v[52:53]
	global_load_dwordx4 v[24:27], v[38:39], off offset:2048
	v_lshl_add_u64 v[82:83], v[62:63], 0, v[52:53]
	global_load_dwordx4 v[28:31], v[28:29], off
	v_mov_b32_e32 v87, v22
	global_load_dwordx4 v[82:85], v[82:83], off
	global_store_dwordx2 v[250:251], v[252:253], off
	v_mov_b32_e32 v22, v21
	v_mov_b32_e32 v86, v20
	v_pk_mul_f32 v[22:23], v[22:23], v[96:97] op_sel_hi:[1,0]
	v_or_b32_e32 v20, v47, v75
	v_pk_mul_f32 v[86:87], v[86:87], v[96:97] op_sel_hi:[1,0]
	v_ashrrev_i32_e32 v21, 31, v20
	v_lshlrev_b64 v[20:21], 14, v[20:21]
	v_lshl_add_u64 v[20:21], s[62:63], 0, v[20:21]
	v_lshl_add_u64 v[20:21], v[20:21], 0, v[34:35]
	v_lshl_add_u64 v[20:21], v[20:21], 0, v[64:65]
	s_waitcnt vmcnt(3)
	v_mov_b32_e32 v89, v26
	v_mov_b32_e32 v26, v25
	s_waitcnt vmcnt(2)
	v_mov_b32_e32 v91, v30
	v_mov_b32_e32 v30, v29
	v_mov_b32_e32 v88, v24
	v_mov_b32_e32 v90, v28
	s_waitcnt vmcnt(1)
	v_mov_b32_e32 v93, v84
	v_mov_b32_e32 v84, v83
	v_pk_mul_f32 v[22:23], v[22:23], v[26:27]
	v_pk_add_f32 v[26:27], v[30:31], 1.0 op_sel_hi:[1,0]
	v_mov_b32_e32 v92, v82
	v_pk_mul_f32 v[24:25], v[86:87], v[88:89]
	v_pk_add_f32 v[28:29], v[90:91], 1.0 op_sel_hi:[1,0]
	v_pk_fma_f32 v[22:23], v[22:23], v[26:27], v[84:85]
	v_pk_fma_f32 v[24:25], v[24:25], v[28:29], v[92:93]
	v_and_b32_sdwa v28, v23, v80 dst_sel:DWORD dst_unused:UNUSED_PAD src0_sel:WORD_1 src1_sel:DWORD
	v_and_b32_sdwa v29, v22, v80 dst_sel:DWORD dst_unused:UNUSED_PAD src0_sel:WORD_1 src1_sel:DWORD
	v_and_b32_sdwa v26, v25, v80 dst_sel:DWORD dst_unused:UNUSED_PAD src0_sel:WORD_1 src1_sel:DWORD
	v_and_b32_sdwa v27, v24, v80 dst_sel:DWORD dst_unused:UNUSED_PAD src0_sel:WORD_1 src1_sel:DWORD
	v_add3_u32 v23, v23, v28, s19
	v_add3_u32 v22, v22, v29, s19
	v_add3_u32 v24, v24, v27, s19
	v_add3_u32 v25, v25, v26, s19
	v_and_b32_e32 v23, 0xffff0000, v23
	v_and_b32_e32 v22, 0xffff0000, v22
	v_or_b32_sdwa v23, v23, v25 dst_sel:DWORD dst_unused:UNUSED_PAD src0_sel:DWORD src1_sel:WORD_1
	v_or_b32_sdwa v22, v22, v24 dst_sel:DWORD dst_unused:UNUSED_PAD src0_sel:DWORD src1_sel:WORD_1
	v_mov_b32_e32 v250, v20
	v_mov_b32_e32 v251, v21
	v_mov_b32_e32 v252, v22
	v_mov_b32_e32 v253, v23
	v_lshl_add_u64 v[24:25], v[60:61], 0, v[56:57]
	global_load_dwordx4 v[20:23], v[38:39], off offset:3072
	v_lshl_add_u64 v[28:29], v[62:63], 0, v[56:57]
	global_load_dwordx4 v[24:27], v[24:25], off
	v_mov_b32_e32 v60, v16
	global_load_dwordx4 v[28:31], v[28:29], off
	global_store_dwordx2 v[250:251], v[252:253], off
	v_or_b32_e32 v16, v47, v76
	v_mov_b32_e32 v61, v18
	v_mov_b32_e32 v18, v17
	v_ashrrev_i32_e32 v17, 31, v16
	v_lshlrev_b64 v[16:17], 14, v[16:17]
	v_lshl_add_u64 v[16:17], s[62:63], 0, v[16:17]
	v_lshl_add_u64 v[16:17], v[16:17], 0, v[34:35]
	v_lshl_add_u64 v[16:17], v[16:17], 0, v[64:65]
	v_pk_mul_f32 v[18:19], v[18:19], v[96:97] op_sel_hi:[1,0]
	v_pk_mul_f32 v[60:61], v[60:61], v[96:97] op_sel_hi:[1,0]
	s_waitcnt vmcnt(3)
	v_mov_b32_e32 v63, v22
	v_mov_b32_e32 v22, v21
	s_waitcnt vmcnt(2)
	v_mov_b32_e32 v65, v26
	v_mov_b32_e32 v26, v25
	v_mov_b32_e32 v62, v20
	v_mov_b32_e32 v64, v24
	s_waitcnt vmcnt(1)
	v_mov_b32_e32 v83, v30
	v_mov_b32_e32 v30, v29
	v_pk_mul_f32 v[18:19], v[18:19], v[22:23]
	v_pk_add_f32 v[22:23], v[26:27], 1.0 op_sel_hi:[1,0]
	v_mov_b32_e32 v82, v28
	v_pk_mul_f32 v[20:21], v[60:61], v[62:63]
	v_pk_add_f32 v[24:25], v[64:65], 1.0 op_sel_hi:[1,0]
	v_pk_fma_f32 v[18:19], v[18:19], v[22:23], v[30:31]
	v_pk_fma_f32 v[20:21], v[20:21], v[24:25], v[82:83]
	v_and_b32_sdwa v24, v19, v80 dst_sel:DWORD dst_unused:UNUSED_PAD src0_sel:WORD_1 src1_sel:DWORD
	v_and_b32_sdwa v25, v18, v80 dst_sel:DWORD dst_unused:UNUSED_PAD src0_sel:WORD_1 src1_sel:DWORD
	v_and_b32_sdwa v22, v21, v80 dst_sel:DWORD dst_unused:UNUSED_PAD src0_sel:WORD_1 src1_sel:DWORD
	v_and_b32_sdwa v23, v20, v80 dst_sel:DWORD dst_unused:UNUSED_PAD src0_sel:WORD_1 src1_sel:DWORD
	v_add3_u32 v19, v19, v24, s19
	v_add3_u32 v18, v18, v25, s19
	v_add3_u32 v20, v20, v23, s19
	v_add3_u32 v21, v21, v22, s19
	v_and_b32_e32 v19, 0xffff0000, v19
	v_and_b32_e32 v18, 0xffff0000, v18
	v_or_b32_sdwa v19, v19, v21 dst_sel:DWORD dst_unused:UNUSED_PAD src0_sel:DWORD src1_sel:WORD_1
	v_or_b32_sdwa v18, v18, v20 dst_sel:DWORD dst_unused:UNUSED_PAD src0_sel:DWORD src1_sel:WORD_1
	global_store_dwordx2 v[16:17], v[18:19], off
	s_and_saveexec_b64 s[0:1], vcc
	s_cbranch_execz .LBB0_1419
; __device__ __forceinline__ u16 f2bf(float x) { unsigned u = __float_as_uint(x); u += 0x7fffu + ((u >> 16) & 1u); return (u16)(u >> 16); }
; __device__ __forceinline__ size_t a_off(int row, int col, int nks) { return ((size_t)((row >> 8) * nks + (col >> 5)) << 13) + ((row & 255) << 5) + swzc(row, col & 31); }
; template <int MODE>
; __device__ __forceinline__ void norm_phase(const Params& p, const float* src, const float* w, const float* modl, int sh_off, int sc_off,
;                            char* smem, int bid, int nblk) {
;     ...
;     float ss = 0.f;
; #pragma unroll
;     for (int i = 0; i < 4; ++i) ss += v[i][0] * v[i][0] + v[i][1] * v[i][1] + v[i][2] * v[i][2] + v[i][3] * v[i][3];
; #pragma unroll
;     for (int o = 32; o >= 1; o >>= 1) ss += __shfl_xor(ss, o);
;     const float rstd = rsqrtf(ss * (1.f / 1024.f) + 1e-6f);
;     const int b = row >> 13;
;     float dots[8];
;     if (MODE == 1) { for (int j = 0; j < 8; ++j) dots[j] = 0.f; }
; #pragma unroll
;     for (int i = 0; i < 4; ++i) {
;       const int c0 = i * 256 + lane * 4;
;       f32x4 ww = *(const f32x4*)(w + c0);
;       f32x4 y;
;       if (MODE == 2) {
; #pragma unroll
;         for (int e = 0; e < 4; ++e) y[e] = v[i][e] * rstd * ww[e];
;         *(f32x4*)(p.out + (size_t)row * 1024 + c0) = y;
;       } else {
;         f32x4 sc = *(const f32x4*)(modl + (size_t)b * 6144 + sc_off + c0);
;         f32x4 sh = *(const f32x4*)(modl + (size_t)b * 6144 + sh_off + c0);
; #pragma unroll
;         for (int e = 0; e < 4; ++e) y[e] = v[i][e] * rstd * ww[e] * (1.f + sc[e]) + sh[e];
;         uint2 pk; pk.x = (unsigned)f2bf(y[0]) | ((unsigned)f2bf(y[1]) << 16); pk.y = (unsigned)f2bf(y[2]) | ((unsigned)f2bf(y[3]) << 16);
;         *(uint2*)(hn + a_off(row, c0, 32)) = pk;
	v_ashrrev_i32_e32 v16, 13, v58
	v_mul_i32_i24_e32 v16, 0x1800, v16
	v_readlane_b32 s20, v244, 23
	v_ashrrev_i32_e32 v17, 31, v16
	v_readlane_b32 s21, v244, 24
	v_mov_b32_e32 v43, v35
	global_load_dwordx4 v[22:25], v[38:39], off
	v_lshl_add_u64 v[18:19], v[16:17], 2, s[20:21]
	v_lshl_add_u64 v[16:17], v[18:19], 0, s[12:13]
	v_lshl_add_u64 v[26:27], v[16:17], 0, v[42:43]
	v_lshl_add_u64 v[18:19], v[18:19], 0, s[14:15]
	global_load_dwordx4 v[26:29], v[26:27], off
	v_lshl_add_u64 v[30:31], v[18:19], 0, v[42:43]
	global_load_dwordx4 v[60:63], v[30:31], off
	v_pk_mul_f32 v[64:65], v[8:9], v[8:9]
	v_pk_mul_f32 v[82:83], v[12:13], v[12:13]
	v_pk_mul_f32 v[20:21], v[14:15], v[14:15]
	v_pk_mul_f32 v[30:31], v[10:11], v[10:11]
	v_mov_b32_e32 v84, v82
	v_mov_b32_e32 v85, v64
	v_mov_b32_e32 v64, v83
	v_pk_add_f32 v[64:65], v[84:85], v[64:65]
	v_mov_b32_e32 v82, v20
	v_mov_b32_e32 v83, v30
	v_pk_add_f32 v[64:65], v[82:83], v[64:65]
	v_mov_b32_e32 v30, v21
	v_pk_add_f32 v[20:21], v[30:31], v[64:65]
	v_mov_b32_e32 v64, v5
	v_mov_b32_e32 v65, v1
	v_mov_b32_e32 v30, v4
	v_mov_b32_e32 v31, v0
	v_pk_mul_f32 v[64:65], v[64:65], v[64:65]
	v_add_f32_e32 v20, v20, v21
	v_pk_fma_f32 v[30:31], v[30:31], v[30:31], v[64:65]
	v_mov_b32_e32 v64, v6
	v_mov_b32_e32 v65, v2
	v_pk_fma_f32 v[30:31], v[64:65], v[64:65], v[30:31]
	v_mov_b32_e32 v64, v7
	v_mov_b32_e32 v65, v3
	v_pk_fma_f32 v[30:31], v[64:65], v[64:65], v[30:31]
	v_ashrrev_i32_e32 v34, 3, v58
	v_add_f32_e32 v20, v30, v20
	v_add_f32_e32 v20, v20, v31
	s_nop 1
	v_mov_b32_e32 v21, v20
	s_nop 1
	v_permlane32_swap_b32_e32 v20, v21
	v_mov_b32_e32 v30, v12
	v_add_u32_e32 v43, s7, v78
	v_add_u32_e32 v47, s6, v77
	v_and_b32_e32 v81, 0xffffffe0, v34
	s_waitcnt lgkmcnt(0)
	v_add_f32_e32 v20, v20, v21
	s_nop 1
	v_mov_b32_e32 v21, v20
	s_nop 1
	v_permlane16_swap_b32_e32 v20, v21
	v_and_b32_e32 v34, 24, v47
	v_or_b32_e32 v58, v81, v72
	v_ashrrev_i32_e32 v59, 31, v58
	v_lshlrev_b64 v[58:59], 14, v[58:59]
	s_waitcnt lgkmcnt(0)
	v_add_f32_e32 v20, v20, v21
	s_nop 1
	v_mov_b32_dpp v31, v20 row_ror:8 row_mask:0xf bank_mask:0xf
	v_lshl_add_u64 v[58:59], s[62:63], 0, v[58:59]
	v_mov_b32_e32 v21, v35
	v_mov_b32_e32 v47, v35
	v_mov_b32_e32 v51, v35
	s_waitcnt lgkmcnt(0)
	v_add_f32_e32 v12, v20, v31
	s_nop 1
	v_mov_b32_dpp v20, v12 row_ror:4 row_mask:0xf bank_mask:0xf
	v_mov_b32_e32 v31, v14
	v_and_b32_e32 v14, 0x1fe0, v43
	v_sub_u32_e32 v43, 0, v34
	v_lshlrev_b32_e32 v34, 1, v14
	s_waitcnt lgkmcnt(0)
	v_add_f32_e32 v12, v12, v20
	s_nop 1
	v_mov_b32_dpp v20, v12 quad_perm:[2,3,0,1] row_mask:0xf bank_mask:0xf
	v_lshl_add_u64 v[58:59], v[58:59], 0, v[34:35]
	v_mov_b32_e32 v55, v35
	s_waitcnt lgkmcnt(0)
	v_add_f32_e32 v12, v12, v20
	s_nop 1
	v_mov_b32_dpp v14, v12 quad_perm:[1,0,3,2] row_mask:0xf bank_mask:0xf
	v_xor_b32_e32 v20, v32, v43
	v_and_or_b32 v20, v20, 24, v73
	v_lshlrev_b32_e32 v20, 1, v20
	v_lshl_add_u64 v[58:59], v[58:59], 0, v[20:21]
	s_waitcnt lgkmcnt(0)
	v_add_f32_e32 v12, v12, v14
	v_fmamk_f32 v12, v12, 0x3a800000, v79
	v_mul_f32_e32 v14, 0x4b800000, v12
	v_cmp_gt_f32_e32 vcc, s18, v12
	s_waitcnt vmcnt(2)
	v_mov_b32_e32 v64, v22
	v_cndmask_b32_e32 v12, v12, v14, vcc
	v_rsq_f32_e32 v12, v12
	v_mov_b32_e32 v65, v24
	v_mov_b32_e32 v24, v23
	v_mul_f32_e32 v14, 0x45800000, v12
	v_cndmask_b32_e32 v12, v12, v14, vcc
	v_pk_mul_f32 v[30:31], v[30:31], v[12:13] op_sel_hi:[1,0]
	v_mov_b32_e32 v14, v13
	v_pk_mul_f32 v[30:31], v[64:65], v[30:31]
	s_waitcnt vmcnt(1)
	v_mov_b32_e32 v65, v28
	v_pk_mul_f32 v[14:15], v[14:15], v[12:13] op_sel_hi:[1,0]
	v_mov_b32_e32 v28, v27
	v_mov_b32_e32 v64, v26
	s_waitcnt vmcnt(0)
	v_mov_b32_e32 v83, v62
	v_pk_mul_f32 v[14:15], v[24:25], v[14:15]
	v_pk_add_f32 v[22:23], v[28:29], 1.0 op_sel_hi:[1,0]
	v_mov_b32_e32 v62, v61
	v_mov_b32_e32 v82, v60
	v_pk_add_f32 v[64:65], v[64:65], 1.0 op_sel_hi:[1,0]
	v_pk_fma_f32 v[14:15], v[22:23], v[14:15], v[62:63]
	v_pk_fma_f32 v[30:31], v[64:65], v[30:31], v[82:83]
	v_and_b32_sdwa v23, v15, v80 dst_sel:DWORD dst_unused:UNUSED_PAD src0_sel:WORD_1 src1_sel:DWORD
	v_and_b32_sdwa v24, v14, v80 dst_sel:DWORD dst_unused:UNUSED_PAD src0_sel:WORD_1 src1_sel:DWORD
	v_and_b32_sdwa v13, v31, v80 dst_sel:DWORD dst_unused:UNUSED_PAD src0_sel:WORD_1 src1_sel:DWORD
	v_and_b32_sdwa v22, v30, v80 dst_sel:DWORD dst_unused:UNUSED_PAD src0_sel:WORD_1 src1_sel:DWORD
	v_add3_u32 v15, v15, v23, s19
	v_add3_u32 v14, v14, v24, s19
	v_add3_u32 v22, v30, v22, s19
	v_add3_u32 v13, v31, v13, s19
	v_and_b32_e32 v15, 0xffff0000, v15
	v_and_b32_e32 v14, 0xffff0000, v14
	v_or_b32_sdwa v15, v15, v13 dst_sel:DWORD dst_unused:UNUSED_PAD src0_sel:DWORD src1_sel:WORD_1
	v_or_b32_sdwa v14, v14, v22 dst_sel:DWORD dst_unused:UNUSED_PAD src0_sel:DWORD src1_sel:WORD_1
	v_mov_b32_e32 v250, v58
	v_mov_b32_e32 v251, v59
	v_mov_b32_e32 v252, v14
	v_mov_b32_e32 v253, v15
	v_lshl_add_u64 v[14:15], v[16:17], 0, v[46:47]
	global_load_dwordx4 v[22:25], v[38:39], off offset:1024
	global_load_dwordx4 v[26:29], v[14:15], off
	v_lshl_add_u64 v[14:15], v[18:19], 0, v[46:47]
	global_load_dwordx4 v[58:61], v[14:15], off
	global_store_dwordx2 v[250:251], v[252:253], off
	v_mov_b32_e32 v15, v10
	v_mov_b32_e32 v10, v9
	v_mov_b32_e32 v14, v8
	v_pk_mul_f32 v[10:11], v[10:11], v[12:13] op_sel_hi:[1,0]
	v_or_b32_e32 v8, v81, v74
	v_pk_mul_f32 v[14:15], v[14:15], v[12:13] op_sel_hi:[1,0]
	v_ashrrev_i32_e32 v9, 31, v8
	v_lshlrev_b64 v[8:9], 14, v[8:9]
	v_lshl_add_u64 v[8:9], s[62:63], 0, v[8:9]
	v_lshl_add_u64 v[8:9], v[8:9], 0, v[34:35]
	v_lshl_add_u64 v[8:9], v[8:9], 0, v[20:21]
	s_waitcnt vmcnt(3)
	v_mov_b32_e32 v31, v24
	s_waitcnt vmcnt(2)
; __device__ __forceinline__ u16 f2bf(float x) { unsigned u = __float_as_uint(x); u += 0x7fffu + ((u >> 16) & 1u); return (u16)(u >> 16); }
; __device__ __forceinline__ size_t a_off(int row, int col, int nks) { return ((size_t)((row >> 8) * nks + (col >> 5)) << 13) + ((row & 255) << 5) + swzc(row, col & 31); }
; template <int MODE>
; __device__ __forceinline__ void norm_phase(const Params& p, const float* src, const float* w, const float* modl, int sh_off, int sc_off,
;                            char* smem, int bid, int nblk) {
;     ...
;       f32x4 ww = *(const f32x4*)(w + c0);
;       f32x4 y;
;       if (MODE == 2) {
; #pragma unroll
;         for (int e = 0; e < 4; ++e) y[e] = v[i][e] * rstd * ww[e];
;         *(f32x4*)(p.out + (size_t)row * 1024 + c0) = y;
;       } else {
;         f32x4 sc = *(const f32x4*)(modl + (size_t)b * 6144 + sc_off + c0);
;         f32x4 sh = *(const f32x4*)(modl + (size_t)b * 6144 + sh_off + c0);
; #pragma unroll
;         for (int e = 0; e < 4; ++e) y[e] = v[i][e] * rstd * ww[e] * (1.f + sc[e]) + sh[e];
;         uint2 pk; pk.x = (unsigned)f2bf(y[0]) | ((unsigned)f2bf(y[1]) << 16); pk.y = (unsigned)f2bf(y[2]) | ((unsigned)f2bf(y[3]) << 16);
;         *(uint2*)(hn + a_off(row, c0, 32)) = pk;
	v_mov_b32_e32 v63, v28
	v_mov_b32_e32 v24, v23
	v_mov_b32_e32 v28, v27
	v_mov_b32_e32 v30, v22
	v_mov_b32_e32 v62, v26
	s_waitcnt vmcnt(1)
	v_mov_b32_e32 v65, v60
	v_mov_b32_e32 v60, v59
	v_pk_mul_f32 v[10:11], v[24:25], v[10:11]
	v_pk_add_f32 v[24:25], v[28:29], 1.0 op_sel_hi:[1,0]
	v_mov_b32_e32 v64, v58
	v_pk_mul_f32 v[14:15], v[30:31], v[14:15]
	v_pk_add_f32 v[22:23], v[62:63], 1.0 op_sel_hi:[1,0]
	v_pk_fma_f32 v[10:11], v[24:25], v[10:11], v[60:61]
	v_pk_fma_f32 v[14:15], v[22:23], v[14:15], v[64:65]
	v_and_b32_sdwa v23, v11, v80 dst_sel:DWORD dst_unused:UNUSED_PAD src0_sel:WORD_1 src1_sel:DWORD
	v_and_b32_sdwa v24, v10, v80 dst_sel:DWORD dst_unused:UNUSED_PAD src0_sel:WORD_1 src1_sel:DWORD
	v_and_b32_sdwa v13, v15, v80 dst_sel:DWORD dst_unused:UNUSED_PAD src0_sel:WORD_1 src1_sel:DWORD
	v_and_b32_sdwa v22, v14, v80 dst_sel:DWORD dst_unused:UNUSED_PAD src0_sel:WORD_1 src1_sel:DWORD
	v_add3_u32 v11, v11, v23, s19
	v_add3_u32 v10, v10, v24, s19
	v_add3_u32 v14, v14, v22, s19
	v_add3_u32 v13, v15, v13, s19
	v_and_b32_e32 v11, 0xffff0000, v11
	v_and_b32_e32 v10, 0xffff0000, v10
	v_or_b32_sdwa v11, v11, v13 dst_sel:DWORD dst_unused:UNUSED_PAD src0_sel:DWORD src1_sel:WORD_1
	v_or_b32_sdwa v10, v10, v14 dst_sel:DWORD dst_unused:UNUSED_PAD src0_sel:DWORD src1_sel:WORD_1
	v_mov_b32_e32 v250, v8
	v_mov_b32_e32 v251, v9
	v_mov_b32_e32 v252, v10
	v_mov_b32_e32 v253, v11
	v_lshl_add_u64 v[14:15], v[16:17], 0, v[50:51]
	global_load_dwordx4 v[8:11], v[38:39], off offset:2048
	global_load_dwordx4 v[22:25], v[14:15], off
	v_lshl_add_u64 v[14:15], v[18:19], 0, v[50:51]
	global_load_dwordx4 v[26:29], v[14:15], off
	global_store_dwordx2 v[250:251], v[252:253], off
	v_mov_b32_e32 v15, v6
	v_mov_b32_e32 v6, v5
	v_mov_b32_e32 v14, v4
	v_pk_mul_f32 v[6:7], v[6:7], v[12:13] op_sel_hi:[1,0]
	v_or_b32_e32 v4, v81, v75
	v_pk_mul_f32 v[14:15], v[14:15], v[12:13] op_sel_hi:[1,0]
	v_ashrrev_i32_e32 v5, 31, v4
	v_lshlrev_b64 v[4:5], 14, v[4:5]
	v_lshl_add_u64 v[4:5], s[62:63], 0, v[4:5]
	v_lshl_add_u64 v[4:5], v[4:5], 0, v[34:35]
	v_lshl_add_u64 v[4:5], v[4:5], 0, v[20:21]
	s_waitcnt vmcnt(3)
	v_mov_b32_e32 v31, v10
	s_waitcnt vmcnt(2)
	v_mov_b32_e32 v59, v24
	v_mov_b32_e32 v10, v9
	v_mov_b32_e32 v24, v23
	v_mov_b32_e32 v30, v8
	v_mov_b32_e32 v58, v22
	s_waitcnt vmcnt(1)
	v_mov_b32_e32 v61, v28
	v_mov_b32_e32 v28, v27
	v_pk_mul_f32 v[6:7], v[6:7], v[10:11]
	v_pk_add_f32 v[10:11], v[24:25], 1.0 op_sel_hi:[1,0]
	v_mov_b32_e32 v60, v26
	v_pk_mul_f32 v[8:9], v[14:15], v[30:31]
	v_pk_add_f32 v[14:15], v[58:59], 1.0 op_sel_hi:[1,0]
	v_pk_fma_f32 v[6:7], v[6:7], v[10:11], v[28:29]
	v_pk_fma_f32 v[8:9], v[8:9], v[14:15], v[60:61]
	v_and_b32_sdwa v13, v7, v80 dst_sel:DWORD dst_unused:UNUSED_PAD src0_sel:WORD_1 src1_sel:DWORD
	v_and_b32_sdwa v14, v6, v80 dst_sel:DWORD dst_unused:UNUSED_PAD src0_sel:WORD_1 src1_sel:DWORD
	v_and_b32_sdwa v10, v9, v80 dst_sel:DWORD dst_unused:UNUSED_PAD src0_sel:WORD_1 src1_sel:DWORD
	v_and_b32_sdwa v11, v8, v80 dst_sel:DWORD dst_unused:UNUSED_PAD src0_sel:WORD_1 src1_sel:DWORD
	v_add3_u32 v7, v7, v13, s19
	v_add3_u32 v6, v6, v14, s19
	v_add3_u32 v8, v8, v11, s19
	v_add3_u32 v9, v9, v10, s19
	v_and_b32_e32 v7, 0xffff0000, v7
	v_and_b32_e32 v6, 0xffff0000, v6
	v_or_b32_sdwa v7, v7, v9 dst_sel:DWORD dst_unused:UNUSED_PAD src0_sel:DWORD src1_sel:WORD_1
	v_or_b32_sdwa v6, v6, v8 dst_sel:DWORD dst_unused:UNUSED_PAD src0_sel:DWORD src1_sel:WORD_1
	v_mov_b32_e32 v250, v4
	v_mov_b32_e32 v251, v5
	v_mov_b32_e32 v252, v6
	v_mov_b32_e32 v253, v7
	v_lshl_add_u64 v[8:9], v[16:17], 0, v[54:55]
	global_load_dwordx4 v[4:7], v[38:39], off offset:3072
	v_lshl_add_u64 v[14:15], v[18:19], 0, v[54:55]
	global_load_dwordx4 v[8:11], v[8:9], off
	v_mov_b32_e32 v18, v0
	global_load_dwordx4 v[14:17], v[14:15], off
	global_store_dwordx2 v[250:251], v[252:253], off
	v_or_b32_e32 v0, v81, v76
	v_mov_b32_e32 v19, v2
	v_mov_b32_e32 v2, v1
	v_ashrrev_i32_e32 v1, 31, v0
	v_lshlrev_b64 v[0:1], 14, v[0:1]
	v_lshl_add_u64 v[0:1], s[62:63], 0, v[0:1]
	v_lshl_add_u64 v[0:1], v[0:1], 0, v[34:35]
	v_lshl_add_u64 v[0:1], v[0:1], 0, v[20:21]
	v_pk_mul_f32 v[18:19], v[18:19], v[12:13] op_sel_hi:[1,0]
	v_pk_mul_f32 v[2:3], v[2:3], v[12:13] op_sel_hi:[1,0]
	s_waitcnt vmcnt(3)
	v_mov_b32_e32 v13, v6
	v_mov_b32_e32 v6, v5
	s_waitcnt vmcnt(2)
	v_mov_b32_e32 v21, v10
	v_mov_b32_e32 v10, v9
	v_mov_b32_e32 v12, v4
	v_mov_b32_e32 v20, v8
	s_waitcnt vmcnt(1)
	v_mov_b32_e32 v23, v16
	v_mov_b32_e32 v16, v15
	v_pk_mul_f32 v[2:3], v[2:3], v[6:7]
	v_pk_add_f32 v[6:7], v[10:11], 1.0 op_sel_hi:[1,0]
	v_mov_b32_e32 v22, v14
	v_pk_mul_f32 v[4:5], v[18:19], v[12:13]
	v_pk_add_f32 v[8:9], v[20:21], 1.0 op_sel_hi:[1,0]
	v_pk_fma_f32 v[2:3], v[2:3], v[6:7], v[16:17]
	v_pk_fma_f32 v[4:5], v[4:5], v[8:9], v[22:23]
	v_and_b32_sdwa v8, v3, v80 dst_sel:DWORD dst_unused:UNUSED_PAD src0_sel:WORD_1 src1_sel:DWORD
	v_and_b32_sdwa v9, v2, v80 dst_sel:DWORD dst_unused:UNUSED_PAD src0_sel:WORD_1 src1_sel:DWORD
	v_and_b32_sdwa v6, v5, v80 dst_sel:DWORD dst_unused:UNUSED_PAD src0_sel:WORD_1 src1_sel:DWORD
	v_and_b32_sdwa v7, v4, v80 dst_sel:DWORD dst_unused:UNUSED_PAD src0_sel:WORD_1 src1_sel:DWORD
	v_add3_u32 v3, v3, v8, s19
	v_add3_u32 v2, v2, v9, s19
	v_add3_u32 v4, v4, v7, s19
	v_add3_u32 v5, v5, v6, s19
	v_and_b32_e32 v3, 0xffff0000, v3
	v_and_b32_e32 v2, 0xffff0000, v2
	v_or_b32_sdwa v3, v3, v5 dst_sel:DWORD dst_unused:UNUSED_PAD src0_sel:DWORD src1_sel:WORD_1
	v_or_b32_sdwa v2, v2, v4 dst_sel:DWORD dst_unused:UNUSED_PAD src0_sel:DWORD src1_sel:WORD_1
	global_store_dwordx2 v[0:1], v[2:3], off
	s_branch .LBB0_1419

; __device__ __forceinline__ u16 f2bf(float x) { unsigned u = __float_as_uint(x); u += 0x7fffu + ((u >> 16) & 1u); return (u16)(u >> 16); }
; __device__ __forceinline__ size_t a_off(int row, int col, int nks) { return ((size_t)((row >> 8) * nks + (col >> 5)) << 13) + ((row & 255) << 5) + swzc(row, col & 31); }
; template <int MODE>
; __device__ __forceinline__ void norm_phase(const Params& p, const float* src, const float* w, const float* modl, int sh_off, int sc_off,
;                            char* smem, int bid, int nblk) {
;     ...
;     float ss = 0.f;
; #pragma unroll
;     for (int i = 0; i < 4; ++i) ss += v[i][0] * v[i][0] + v[i][1] * v[i][1] + v[i][2] * v[i][2] + v[i][3] * v[i][3];
; #pragma unroll
;     for (int o = 32; o >= 1; o >>= 1) ss += __shfl_xor(ss, o);
;     const float rstd = rsqrtf(ss * (1.f / 1024.f) + 1e-6f);
;     const int b = row >> 13;
;     float dots[8];
;     if (MODE == 1) { for (int j = 0; j < 8; ++j) dots[j] = 0.f; }
; #pragma unroll
;     for (int i = 0; i < 4; ++i) {
;       const int c0 = i * 256 + lane * 4;
;       f32x4 ww = *(const f32x4*)(w + c0);
;       f32x4 y;
;       if (MODE == 2) {
; #pragma unroll
;         for (int e = 0; e < 4; ++e) y[e] = v[i][e] * rstd * ww[e];
;         *(f32x4*)(p.out + (size_t)row * 1024 + c0) = y;
;       } else {
;         f32x4 sc = *(const f32x4*)(modl + (size_t)b * 6144 + sc_off + c0);
;         f32x4 sh = *(const f32x4*)(modl + (size_t)b * 6144 + sh_off + c0);
; #pragma unroll
;         for (int e = 0; e < 4; ++e) y[e] = v[i][e] * rstd * ww[e] * (1.f + sc[e]) + sh[e];
;         uint2 pk; pk.x = (unsigned)f2bf(y[0]) | ((unsigned)f2bf(y[1]) << 16); pk.y = (unsigned)f2bf(y[2]) | ((unsigned)f2bf(y[3]) << 16);
;         *(uint2*)(hn + a_off(row, c0, 32)) = pk;
.LBB0_1646:
	s_or_b64 exec, exec, s[0:1]
	v_ashrrev_i32_e32 v34, 13, v33
	v_mul_i32_i24_e32 v66, 0x1800, v34
	v_ashrrev_i32_e32 v67, 31, v66
	v_lshl_add_u64 v[68:69], v[66:67], 2, s[6:7]
	v_lshl_add_u64 v[66:67], v[68:69], 0, s[8:9]
	global_load_dwordx4 v[88:91], v[38:39], off
	v_lshl_add_u64 v[92:93], v[66:67], 0, v[50:51]
	global_load_dwordx4 v[92:95], v[92:93], off
	v_lshl_add_u64 v[68:69], v[68:69], 0, v[50:51]
	global_load_dwordx4 v[96:99], v[68:69], off
	s_waitcnt vmcnt(0)
	v_pk_mul_f32 v[102:103], v[28:29], v[28:29]
	v_pk_mul_f32 v[104:105], v[24:25], v[24:25]
	v_pk_mul_f32 v[70:71], v[30:31], v[30:31]
	v_pk_mul_f32 v[100:101], v[26:27], v[26:27]
	v_mov_b32_e32 v106, v102
	v_mov_b32_e32 v107, v104
	v_mov_b32_e32 v104, v103
	v_pk_add_f32 v[102:103], v[106:107], v[104:105]
	v_mov_b32_e32 v104, v70
	v_mov_b32_e32 v105, v100
	v_pk_add_f32 v[102:103], v[104:105], v[102:103]
	v_mov_b32_e32 v100, v71
	v_pk_add_f32 v[70:71], v[100:101], v[102:103]
	v_mov_b32_e32 v102, v17
	v_mov_b32_e32 v103, v21
	v_mov_b32_e32 v100, v16
	v_mov_b32_e32 v101, v20
	v_pk_mul_f32 v[102:103], v[102:103], v[102:103]
	v_add_f32_e32 v34, v70, v71
	v_pk_fma_f32 v[100:101], v[100:101], v[100:101], v[102:103]
	v_mov_b32_e32 v102, v18
	v_mov_b32_e32 v103, v22
	v_pk_fma_f32 v[100:101], v[102:103], v[102:103], v[100:101]
	v_mov_b32_e32 v102, v19
	v_mov_b32_e32 v103, v23
	v_pk_fma_f32 v[100:101], v[102:103], v[102:103], v[100:101]
	v_and_b32_e32 v61, 24, v83
	v_add_f32_e32 v34, v101, v34
	v_add_f32_e32 v34, v100, v34
	s_nop 1
	v_mov_b32_e32 v49, v34
	s_nop 1
	v_permlane32_swap_b32_e32 v34, v49
	v_mov_b32_e32 v101, v30
	v_mov_b32_e32 v30, v29
	v_and_b32_e32 v57, 0x1fe0, v84
	v_sub_u32_e32 v61, 0, v61
	s_waitcnt lgkmcnt(0)
	v_add_f32_e32 v34, v34, v49
	s_nop 1
	v_mov_b32_e32 v49, v34
	s_nop 1
	v_permlane16_swap_b32_e32 v34, v49
	v_mov_b32_e32 v100, v28
	v_ashrrev_i32_e32 v53, 3, v33
	v_and_b32_e32 v53, 0xffffffe0, v53
	v_or_b32_e32 v28, v53, v78
	s_waitcnt lgkmcnt(0)
	v_add_f32_e32 v34, v34, v49
	s_nop 1
	v_mov_b32_dpp v49, v34 row_ror:8 row_mask:0xf bank_mask:0xf
	v_mov_b32_e32 v71, v35
	s_waitcnt lgkmcnt(0)
	v_add_f32_e32 v34, v34, v49
	s_nop 1
	v_mov_b32_dpp v49, v34 row_ror:4 row_mask:0xf bank_mask:0xf
	s_waitcnt lgkmcnt(0)
	v_add_f32_e32 v29, v34, v49
	s_nop 1
	v_mov_b32_dpp v49, v29 quad_perm:[2,3,0,1] row_mask:0xf bank_mask:0xf
	v_lshlrev_b32_e32 v34, 1, v57
	v_xor_b32_e32 v57, v32, v61
	v_and_or_b32 v57, v57, 24, v79
	v_lshlrev_b32_e32 v70, 1, v57
	s_waitcnt lgkmcnt(0)
	v_add_f32_e32 v49, v29, v49
	s_nop 1
	v_mov_b32_dpp v61, v49 quad_perm:[1,0,3,2] row_mask:0xf bank_mask:0xf
	v_ashrrev_i32_e32 v29, 31, v28
	v_lshlrev_b64 v[28:29], 14, v[28:29]
	v_lshl_add_u64 v[28:29], s[62:63], 0, v[28:29]
	v_lshl_add_u64 v[28:29], v[28:29], 0, v[34:35]
	s_waitcnt lgkmcnt(0)
	v_add_f32_e32 v49, v49, v61
	v_fmamk_f32 v49, v49, 0x3a800000, v85
	v_mul_f32_e32 v57, 0x4b800000, v49
	v_cmp_gt_f32_e64 s[0:1], s18, v49
	v_lshl_add_u64 v[28:29], v[28:29], 0, v[70:71]
	v_mov_b32_e32 v105, v90
	v_cndmask_b32_e64 v49, v49, v57, s[0:1]
	v_rsq_f32_e32 v49, v49
	v_mov_b32_e32 v90, v89
	v_mov_b32_e32 v104, v88
	v_mul_f32_e32 v57, 0x45800000, v49
	v_cndmask_b32_e64 v102, v49, v57, s[0:1]
	v_pk_mul_f32 v[30:31], v[30:31], v[102:103] op_sel_hi:[1,0]
	v_pk_mul_f32 v[100:101], v[100:101], v[102:103] op_sel_hi:[1,0]
	v_pk_mul_f32 v[30:31], v[90:91], v[30:31]
	v_mov_b32_e32 v90, v92
	v_mov_b32_e32 v91, v94
	v_pk_mul_f32 v[88:89], v[104:105], v[100:101]
	v_mov_b32_e32 v100, v96
	v_mov_b32_e32 v101, v98
	v_pk_add_f32 v[90:91], v[90:91], 1.0 op_sel_hi:[1,0]
	v_mov_b32_e32 v94, v93
	v_pk_fma_f32 v[88:89], v[90:91], v[88:89], v[100:101]
	v_pk_add_f32 v[90:91], v[94:95], 1.0 op_sel_hi:[1,0]
	v_mov_b32_e32 v98, v97
	v_pk_fma_f32 v[30:31], v[90:91], v[30:31], v[98:99]
	v_and_b32_sdwa v49, v89, v86 dst_sel:DWORD dst_unused:UNUSED_PAD src0_sel:WORD_1 src1_sel:DWORD
	v_and_b32_sdwa v61, v31, v86 dst_sel:DWORD dst_unused:UNUSED_PAD src0_sel:WORD_1 src1_sel:DWORD
	v_and_b32_sdwa v65, v30, v86 dst_sel:DWORD dst_unused:UNUSED_PAD src0_sel:WORD_1 src1_sel:DWORD
	v_and_b32_sdwa v57, v88, v86 dst_sel:DWORD dst_unused:UNUSED_PAD src0_sel:WORD_1 src1_sel:DWORD
	v_add3_u32 v31, v31, v61, s19
	v_add3_u32 v30, v30, v65, s19
	v_add3_u32 v57, v88, v57, s19
	v_add3_u32 v49, v89, v49, s19
	v_and_b32_e32 v31, 0xffff0000, v31
	v_and_b32_e32 v30, 0xffff0000, v30
	v_or_b32_sdwa v31, v31, v49 dst_sel:DWORD dst_unused:UNUSED_PAD src0_sel:DWORD src1_sel:WORD_1
	v_or_b32_sdwa v30, v30, v57 dst_sel:DWORD dst_unused:UNUSED_PAD src0_sel:DWORD src1_sel:WORD_1
	v_mov_b32_e32 v250, v28
	v_mov_b32_e32 v251, v29
	v_mov_b32_e32 v252, v30
	v_mov_b32_e32 v253, v31
	global_load_dwordx4 v[28:31], v[40:41], off
	v_lshl_add_u64 v[96:97], v[66:67], 0, v[54:55]
	global_load_dwordx4 v[88:91], v[96:97], off
	global_load_dwordx4 v[92:95], v[68:69], off offset:1024
	global_store_dwordx2 v[250:251], v[252:253], off
	v_mov_b32_e32 v97, v26
	v_mov_b32_e32 v26, v25
	v_mov_b32_e32 v96, v24
	v_pk_mul_f32 v[26:27], v[26:27], v[102:103] op_sel_hi:[1,0]
	v_or_b32_e32 v24, v53, v80
	v_pk_mul_f32 v[96:97], v[96:97], v[102:103] op_sel_hi:[1,0]
	v_ashrrev_i32_e32 v25, 31, v24
	v_lshlrev_b64 v[24:25], 14, v[24:25]
	v_lshl_add_u64 v[24:25], s[62:63], 0, v[24:25]
	v_lshl_add_u64 v[24:25], v[24:25], 0, v[34:35]
	v_lshl_add_u64 v[24:25], v[24:25], 0, v[70:71]
	s_waitcnt vmcnt(3)
	v_mov_b32_e32 v99, v30
	s_waitcnt vmcnt(2)
	v_mov_b32_e32 v101, v90
	v_mov_b32_e32 v30, v29
	v_mov_b32_e32 v90, v89
	v_mov_b32_e32 v98, v28
	v_mov_b32_e32 v100, v88
	s_waitcnt vmcnt(1)
; __device__ __forceinline__ u16 f2bf(float x) { unsigned u = __float_as_uint(x); u += 0x7fffu + ((u >> 16) & 1u); return (u16)(u >> 16); }
; __device__ __forceinline__ size_t a_off(int row, int col, int nks) { return ((size_t)((row >> 8) * nks + (col >> 5)) << 13) + ((row & 255) << 5) + swzc(row, col & 31); }
; template <int MODE>
; __device__ __forceinline__ void norm_phase(const Params& p, const float* src, const float* w, const float* modl, int sh_off, int sc_off,
;                            char* smem, int bid, int nblk) {
;     ...
;       f32x4 ww = *(const f32x4*)(w + c0);
;       f32x4 y;
;       if (MODE == 2) {
; #pragma unroll
;         for (int e = 0; e < 4; ++e) y[e] = v[i][e] * rstd * ww[e];
;         *(f32x4*)(p.out + (size_t)row * 1024 + c0) = y;
;       } else {
;         f32x4 sc = *(const f32x4*)(modl + (size_t)b * 6144 + sc_off + c0);
;         f32x4 sh = *(const f32x4*)(modl + (size_t)b * 6144 + sh_off + c0);
; #pragma unroll
;         for (int e = 0; e < 4; ++e) y[e] = v[i][e] * rstd * ww[e] * (1.f + sc[e]) + sh[e];
;         uint2 pk; pk.x = (unsigned)f2bf(y[0]) | ((unsigned)f2bf(y[1]) << 16); pk.y = (unsigned)f2bf(y[2]) | ((unsigned)f2bf(y[3]) << 16);
;         *(uint2*)(hn + a_off(row, c0, 32)) = pk;
	v_mov_b32_e32 v105, v94
	v_mov_b32_e32 v94, v93
	v_pk_mul_f32 v[26:27], v[30:31], v[26:27]
	v_pk_add_f32 v[30:31], v[90:91], 1.0 op_sel_hi:[1,0]
	v_mov_b32_e32 v104, v92
	v_pk_mul_f32 v[28:29], v[98:99], v[96:97]
	v_pk_add_f32 v[88:89], v[100:101], 1.0 op_sel_hi:[1,0]
	v_pk_fma_f32 v[26:27], v[30:31], v[26:27], v[94:95]
	v_pk_fma_f32 v[28:29], v[88:89], v[28:29], v[104:105]
	v_and_b32_sdwa v49, v27, v86 dst_sel:DWORD dst_unused:UNUSED_PAD src0_sel:WORD_1 src1_sel:DWORD
	v_and_b32_sdwa v57, v26, v86 dst_sel:DWORD dst_unused:UNUSED_PAD src0_sel:WORD_1 src1_sel:DWORD
	v_and_b32_sdwa v30, v29, v86 dst_sel:DWORD dst_unused:UNUSED_PAD src0_sel:WORD_1 src1_sel:DWORD
	v_and_b32_sdwa v31, v28, v86 dst_sel:DWORD dst_unused:UNUSED_PAD src0_sel:WORD_1 src1_sel:DWORD
	v_add3_u32 v27, v27, v49, s19
	v_add3_u32 v26, v26, v57, s19
	v_add3_u32 v28, v28, v31, s19
	v_add3_u32 v29, v29, v30, s19
	v_and_b32_e32 v27, 0xffff0000, v27
	v_and_b32_e32 v26, 0xffff0000, v26
	v_or_b32_sdwa v27, v27, v29 dst_sel:DWORD dst_unused:UNUSED_PAD src0_sel:DWORD src1_sel:WORD_1
	v_or_b32_sdwa v26, v26, v28 dst_sel:DWORD dst_unused:UNUSED_PAD src0_sel:DWORD src1_sel:WORD_1
	v_mov_b32_e32 v250, v24
	v_mov_b32_e32 v251, v25
	v_mov_b32_e32 v252, v26
	v_mov_b32_e32 v253, v27
	global_load_dwordx4 v[24:27], v[42:43], off
	v_lshl_add_u64 v[92:93], v[66:67], 0, v[58:59]
	global_load_dwordx4 v[28:31], v[92:93], off
	global_load_dwordx4 v[88:91], v[68:69], off offset:2048
	global_store_dwordx2 v[250:251], v[252:253], off
	v_mov_b32_e32 v93, v22
	v_mov_b32_e32 v22, v21
	v_mov_b32_e32 v92, v20
	v_pk_mul_f32 v[22:23], v[22:23], v[102:103] op_sel_hi:[1,0]
	v_or_b32_e32 v20, v53, v81
	v_pk_mul_f32 v[92:93], v[92:93], v[102:103] op_sel_hi:[1,0]
	v_ashrrev_i32_e32 v21, 31, v20
	v_lshlrev_b64 v[20:21], 14, v[20:21]
	v_lshl_add_u64 v[20:21], s[62:63], 0, v[20:21]
	v_lshl_add_u64 v[20:21], v[20:21], 0, v[34:35]
	v_lshl_add_u64 v[20:21], v[20:21], 0, v[70:71]
	v_lshl_add_u64 v[66:67], v[66:67], 0, v[62:63]
	s_waitcnt vmcnt(3)
	v_mov_b32_e32 v95, v26
	s_waitcnt vmcnt(2)
	v_mov_b32_e32 v97, v30
	v_mov_b32_e32 v26, v25
	v_mov_b32_e32 v30, v29
	v_mov_b32_e32 v94, v24
	v_mov_b32_e32 v96, v28
	s_waitcnt vmcnt(1)
	v_mov_b32_e32 v99, v90
	v_mov_b32_e32 v90, v89
	v_pk_mul_f32 v[22:23], v[22:23], v[26:27]
	v_pk_add_f32 v[26:27], v[30:31], 1.0 op_sel_hi:[1,0]
	v_mov_b32_e32 v98, v88
	v_pk_mul_f32 v[24:25], v[92:93], v[94:95]
	v_pk_add_f32 v[28:29], v[96:97], 1.0 op_sel_hi:[1,0]
	v_pk_fma_f32 v[22:23], v[22:23], v[26:27], v[90:91]
	v_pk_fma_f32 v[24:25], v[24:25], v[28:29], v[98:99]
	v_and_b32_sdwa v28, v23, v86 dst_sel:DWORD dst_unused:UNUSED_PAD src0_sel:WORD_1 src1_sel:DWORD
	v_and_b32_sdwa v29, v22, v86 dst_sel:DWORD dst_unused:UNUSED_PAD src0_sel:WORD_1 src1_sel:DWORD
	v_and_b32_sdwa v26, v25, v86 dst_sel:DWORD dst_unused:UNUSED_PAD src0_sel:WORD_1 src1_sel:DWORD
	v_and_b32_sdwa v27, v24, v86 dst_sel:DWORD dst_unused:UNUSED_PAD src0_sel:WORD_1 src1_sel:DWORD
	v_add3_u32 v23, v23, v28, s19
	v_add3_u32 v22, v22, v29, s19
	v_add3_u32 v24, v24, v27, s19
	v_add3_u32 v25, v25, v26, s19
	v_and_b32_e32 v23, 0xffff0000, v23
	v_and_b32_e32 v22, 0xffff0000, v22
	v_or_b32_sdwa v23, v23, v25 dst_sel:DWORD dst_unused:UNUSED_PAD src0_sel:DWORD src1_sel:WORD_1
	v_or_b32_sdwa v22, v22, v24 dst_sel:DWORD dst_unused:UNUSED_PAD src0_sel:DWORD src1_sel:WORD_1
	global_store_dwordx2 v[20:21], v[22:23], off
	global_load_dwordx4 v[20:23], v[44:45], off
	s_nop 0
	global_load_dwordx4 v[24:27], v[66:67], off
	global_load_dwordx4 v[28:31], v[68:69], off offset:3072
	v_mov_b32_e32 v66, v16
	v_or_b32_e32 v16, v53, v82
	v_mov_b32_e32 v67, v18
	v_mov_b32_e32 v18, v17
	v_ashrrev_i32_e32 v17, 31, v16
	v_lshlrev_b64 v[16:17], 14, v[16:17]
	v_lshl_add_u64 v[16:17], s[62:63], 0, v[16:17]
	v_lshl_add_u64 v[16:17], v[16:17], 0, v[34:35]
	v_lshl_add_u64 v[16:17], v[16:17], 0, v[70:71]
	v_pk_mul_f32 v[18:19], v[18:19], v[102:103] op_sel_hi:[1,0]
	v_pk_mul_f32 v[66:67], v[66:67], v[102:103] op_sel_hi:[1,0]
	s_waitcnt vmcnt(1)
	v_mov_b32_e32 v71, v26
	v_mov_b32_e32 v69, v22
	v_mov_b32_e32 v22, v21
	v_mov_b32_e32 v26, v25
	v_mov_b32_e32 v68, v20
	v_mov_b32_e32 v70, v24
	s_waitcnt vmcnt(0)
	v_mov_b32_e32 v89, v30
	v_mov_b32_e32 v30, v29
	v_pk_mul_f32 v[18:19], v[18:19], v[22:23]
	v_pk_add_f32 v[22:23], v[26:27], 1.0 op_sel_hi:[1,0]
	v_mov_b32_e32 v88, v28
	v_pk_mul_f32 v[20:21], v[66:67], v[68:69]
	v_pk_add_f32 v[24:25], v[70:71], 1.0 op_sel_hi:[1,0]
	v_pk_fma_f32 v[18:19], v[18:19], v[22:23], v[30:31]
	v_pk_fma_f32 v[20:21], v[20:21], v[24:25], v[88:89]
	v_and_b32_sdwa v24, v19, v86 dst_sel:DWORD dst_unused:UNUSED_PAD src0_sel:WORD_1 src1_sel:DWORD
	v_and_b32_sdwa v25, v18, v86 dst_sel:DWORD dst_unused:UNUSED_PAD src0_sel:WORD_1 src1_sel:DWORD
	v_and_b32_sdwa v22, v21, v86 dst_sel:DWORD dst_unused:UNUSED_PAD src0_sel:WORD_1 src1_sel:DWORD
	v_and_b32_sdwa v23, v20, v86 dst_sel:DWORD dst_unused:UNUSED_PAD src0_sel:WORD_1 src1_sel:DWORD
	v_add3_u32 v19, v19, v24, s19
	v_add3_u32 v18, v18, v25, s19
	v_add3_u32 v20, v20, v23, s19
	v_add3_u32 v21, v21, v22, s19
	v_and_b32_e32 v19, 0xffff0000, v19
	v_and_b32_e32 v18, 0xffff0000, v18
	v_or_b32_sdwa v19, v19, v21 dst_sel:DWORD dst_unused:UNUSED_PAD src0_sel:DWORD src1_sel:WORD_1
	v_or_b32_sdwa v18, v18, v20 dst_sel:DWORD dst_unused:UNUSED_PAD src0_sel:DWORD src1_sel:WORD_1
	global_store_dwordx2 v[16:17], v[18:19], off
	s_and_saveexec_b64 s[0:1], vcc
	s_cbranch_execz .LBB0_1637
; __device__ __forceinline__ u16 f2bf(float x) { unsigned u = __float_as_uint(x); u += 0x7fffu + ((u >> 16) & 1u); return (u16)(u >> 16); }
; __device__ __forceinline__ size_t a_off(int row, int col, int nks) { return ((size_t)((row >> 8) * nks + (col >> 5)) << 13) + ((row & 255) << 5) + swzc(row, col & 31); }
; template <int MODE>
; __device__ __forceinline__ void norm_phase(const Params& p, const float* src, const float* w, const float* modl, int sh_off, int sc_off,
;                            char* smem, int bid, int nblk) {
;     ...
;     float ss = 0.f;
; #pragma unroll
;     for (int i = 0; i < 4; ++i) ss += v[i][0] * v[i][0] + v[i][1] * v[i][1] + v[i][2] * v[i][2] + v[i][3] * v[i][3];
; #pragma unroll
;     for (int o = 32; o >= 1; o >>= 1) ss += __shfl_xor(ss, o);
;     const float rstd = rsqrtf(ss * (1.f / 1024.f) + 1e-6f);
;     const int b = row >> 13;
;     float dots[8];
;     if (MODE == 1) { for (int j = 0; j < 8; ++j) dots[j] = 0.f; }
; #pragma unroll
;     for (int i = 0; i < 4; ++i) {
;       const int c0 = i * 256 + lane * 4;
;       f32x4 ww = *(const f32x4*)(w + c0);
;       f32x4 y;
;       if (MODE == 2) {
; #pragma unroll
;         for (int e = 0; e < 4; ++e) y[e] = v[i][e] * rstd * ww[e];
;         *(f32x4*)(p.out + (size_t)row * 1024 + c0) = y;
;       } else {
;         f32x4 sc = *(const f32x4*)(modl + (size_t)b * 6144 + sc_off + c0);
;         f32x4 sh = *(const f32x4*)(modl + (size_t)b * 6144 + sh_off + c0);
; #pragma unroll
;         for (int e = 0; e < 4; ++e) y[e] = v[i][e] * rstd * ww[e] * (1.f + sc[e]) + sh[e];
;         uint2 pk; pk.x = (unsigned)f2bf(y[0]) | ((unsigned)f2bf(y[1]) << 16); pk.y = (unsigned)f2bf(y[2]) | ((unsigned)f2bf(y[3]) << 16);
;         *(uint2*)(hn + a_off(row, c0, 32)) = pk;
	v_ashrrev_i32_e32 v16, 13, v64
	v_mul_i32_i24_e32 v16, 0x1800, v16
	v_ashrrev_i32_e32 v17, 31, v16
	v_lshl_add_u64 v[18:19], v[16:17], 2, s[6:7]
	v_lshl_add_u64 v[16:17], v[18:19], 0, s[8:9]
	v_mov_b32_e32 v49, v35
	global_load_dwordx4 v[22:25], v[38:39], off
	v_lshl_add_u64 v[26:27], v[16:17], 0, v[48:49]
	global_load_dwordx4 v[26:29], v[26:27], off
	v_lshl_add_u64 v[18:19], v[18:19], 0, v[48:49]
	global_load_dwordx4 v[66:69], v[18:19], off
	v_pk_mul_f32 v[70:71], v[8:9], v[8:9]
	v_pk_mul_f32 v[88:89], v[12:13], v[12:13]
	v_pk_mul_f32 v[20:21], v[14:15], v[14:15]
	v_pk_mul_f32 v[30:31], v[10:11], v[10:11]
	v_mov_b32_e32 v90, v88
	v_mov_b32_e32 v91, v70
	v_mov_b32_e32 v70, v89
	v_pk_add_f32 v[70:71], v[90:91], v[70:71]
	v_mov_b32_e32 v88, v20
	v_mov_b32_e32 v89, v30
	v_pk_add_f32 v[70:71], v[88:89], v[70:71]
	v_mov_b32_e32 v30, v21
	v_pk_add_f32 v[20:21], v[30:31], v[70:71]
	v_mov_b32_e32 v70, v5
	v_mov_b32_e32 v71, v1
	v_mov_b32_e32 v30, v4
	v_mov_b32_e32 v31, v0
	v_pk_mul_f32 v[70:71], v[70:71], v[70:71]
	v_add_f32_e32 v20, v20, v21
	v_pk_fma_f32 v[30:31], v[30:31], v[30:31], v[70:71]
	v_mov_b32_e32 v70, v6
	v_mov_b32_e32 v71, v2
	v_pk_fma_f32 v[30:31], v[70:71], v[70:71], v[30:31]
	v_mov_b32_e32 v70, v7
	v_mov_b32_e32 v71, v3
	v_pk_fma_f32 v[30:31], v[70:71], v[70:71], v[30:31]
	v_add_u32_e32 v49, s11, v84
	v_add_f32_e32 v20, v30, v20
	v_add_f32_e32 v20, v20, v31
	s_nop 1
	v_mov_b32_e32 v21, v20
	s_nop 1
	v_permlane32_swap_b32_e32 v20, v21
	v_mov_b32_e32 v30, v12
	v_mov_b32_e32 v31, v14
	v_mov_b32_e32 v14, v13
	v_and_b32_e32 v13, 0x1fe0, v49
	s_waitcnt lgkmcnt(0)
	v_add_f32_e32 v20, v20, v21
	s_nop 1
	v_mov_b32_e32 v21, v20
	s_nop 1
	v_permlane16_swap_b32_e32 v20, v21
	v_ashrrev_i32_e32 v34, 3, v64
	v_add_u32_e32 v57, s10, v83
	v_and_b32_e32 v87, 0xffffffe0, v34
	v_and_b32_e32 v34, 24, v57
	s_waitcnt lgkmcnt(0)
	v_add_f32_e32 v20, v20, v21
	s_nop 1
	v_mov_b32_dpp v53, v20 row_ror:8 row_mask:0xf bank_mask:0xf
	v_mov_b32_e32 v21, v35
	v_mov_b32_e32 v57, v35
	v_mov_b32_e32 v61, v35
	s_waitcnt lgkmcnt(0)
	v_add_f32_e32 v12, v20, v53
	s_nop 1
	v_mov_b32_dpp v20, v12 row_ror:4 row_mask:0xf bank_mask:0xf
	v_sub_u32_e32 v53, 0, v34
	v_lshlrev_b32_e32 v34, 1, v13
	v_xor_b32_e32 v53, v32, v53
	v_and_or_b32 v53, v53, 24, v79
	s_waitcnt lgkmcnt(0)
	v_add_f32_e32 v20, v12, v20
	s_nop 1
	v_mov_b32_dpp v49, v20 quad_perm:[2,3,0,1] row_mask:0xf bank_mask:0xf
	v_or_b32_e32 v12, v87, v78
	v_ashrrev_i32_e32 v13, 31, v12
	v_lshlrev_b64 v[12:13], 14, v[12:13]
	v_lshl_add_u64 v[12:13], s[62:63], 0, v[12:13]
	s_waitcnt lgkmcnt(0)
	v_add_f32_e32 v20, v20, v49
	s_nop 1
	v_mov_b32_dpp v49, v20 quad_perm:[1,0,3,2] row_mask:0xf bank_mask:0xf
	v_lshl_add_u64 v[12:13], v[12:13], 0, v[34:35]
	s_waitcnt lgkmcnt(0)
	v_add_f32_e32 v20, v20, v49
	v_fmamk_f32 v20, v20, 0x3a800000, v85
	v_mul_f32_e32 v49, 0x4b800000, v20
	v_cmp_gt_f32_e32 vcc, s18, v20
	s_waitcnt vmcnt(2)
	v_mov_b32_e32 v70, v22
	v_cndmask_b32_e32 v20, v20, v49, vcc
	v_rsq_f32_e32 v49, v20
	v_lshlrev_b32_e32 v20, 1, v53
	v_lshl_add_u64 v[64:65], v[12:13], 0, v[20:21]
	v_mov_b32_e32 v71, v24
	v_mul_f32_e32 v12, 0x45800000, v49
	v_cndmask_b32_e32 v12, v49, v12, vcc
	v_pk_mul_f32 v[30:31], v[30:31], v[12:13] op_sel_hi:[1,0]
	v_pk_mul_f32 v[14:15], v[14:15], v[12:13] op_sel_hi:[1,0]
	v_pk_mul_f32 v[30:31], v[70:71], v[30:31]
	s_waitcnt vmcnt(1)
	v_mov_b32_e32 v71, v28
	v_mov_b32_e32 v24, v23
	v_mov_b32_e32 v28, v27
	v_mov_b32_e32 v70, v26
	s_waitcnt vmcnt(0)
	v_mov_b32_e32 v89, v68
	v_pk_mul_f32 v[14:15], v[24:25], v[14:15]
	v_pk_add_f32 v[22:23], v[28:29], 1.0 op_sel_hi:[1,0]
	v_mov_b32_e32 v68, v67
	v_mov_b32_e32 v88, v66
	v_pk_add_f32 v[70:71], v[70:71], 1.0 op_sel_hi:[1,0]
	v_pk_fma_f32 v[14:15], v[22:23], v[14:15], v[68:69]
	v_pk_fma_f32 v[30:31], v[70:71], v[30:31], v[88:89]
	v_and_b32_sdwa v23, v15, v86 dst_sel:DWORD dst_unused:UNUSED_PAD src0_sel:WORD_1 src1_sel:DWORD
	v_and_b32_sdwa v24, v14, v86 dst_sel:DWORD dst_unused:UNUSED_PAD src0_sel:WORD_1 src1_sel:DWORD
	v_and_b32_sdwa v13, v31, v86 dst_sel:DWORD dst_unused:UNUSED_PAD src0_sel:WORD_1 src1_sel:DWORD
	v_and_b32_sdwa v22, v30, v86 dst_sel:DWORD dst_unused:UNUSED_PAD src0_sel:WORD_1 src1_sel:DWORD
	v_add3_u32 v15, v15, v23, s19
	v_add3_u32 v14, v14, v24, s19
	v_add3_u32 v22, v30, v22, s19
	v_add3_u32 v13, v31, v13, s19
	v_and_b32_e32 v15, 0xffff0000, v15
	v_and_b32_e32 v14, 0xffff0000, v14
	v_or_b32_sdwa v15, v15, v13 dst_sel:DWORD dst_unused:UNUSED_PAD src0_sel:DWORD src1_sel:WORD_1
	v_or_b32_sdwa v14, v14, v22 dst_sel:DWORD dst_unused:UNUSED_PAD src0_sel:DWORD src1_sel:WORD_1
	v_mov_b32_e32 v250, v64
	v_mov_b32_e32 v251, v65
	v_mov_b32_e32 v252, v14
	v_mov_b32_e32 v253, v15
	v_mov_b32_e32 v53, v35
	global_load_dwordx4 v[22:25], v[40:41], off
	v_lshl_add_u64 v[14:15], v[16:17], 0, v[52:53]
	global_load_dwordx4 v[26:29], v[14:15], off
	global_load_dwordx4 v[64:67], v[18:19], off offset:1024
	global_store_dwordx2 v[250:251], v[252:253], off
	v_mov_b32_e32 v15, v10
	v_mov_b32_e32 v10, v9
	v_mov_b32_e32 v14, v8
	v_pk_mul_f32 v[10:11], v[10:11], v[12:13] op_sel_hi:[1,0]
	v_or_b32_e32 v8, v87, v80
	v_pk_mul_f32 v[14:15], v[14:15], v[12:13] op_sel_hi:[1,0]
	v_ashrrev_i32_e32 v9, 31, v8
	v_lshlrev_b64 v[8:9], 14, v[8:9]
	v_lshl_add_u64 v[8:9], s[62:63], 0, v[8:9]
	v_lshl_add_u64 v[8:9], v[8:9], 0, v[34:35]
	v_lshl_add_u64 v[8:9], v[8:9], 0, v[20:21]
	s_waitcnt vmcnt(3)
	v_mov_b32_e32 v31, v24
	s_waitcnt vmcnt(2)
; __device__ __forceinline__ u16 f2bf(float x) { unsigned u = __float_as_uint(x); u += 0x7fffu + ((u >> 16) & 1u); return (u16)(u >> 16); }
; __device__ __forceinline__ size_t a_off(int row, int col, int nks) { return ((size_t)((row >> 8) * nks + (col >> 5)) << 13) + ((row & 255) << 5) + swzc(row, col & 31); }
; template <int MODE>
; __device__ __forceinline__ void norm_phase(const Params& p, const float* src, const float* w, const float* modl, int sh_off, int sc_off,
;                            char* smem, int bid, int nblk) {
;     ...
;       f32x4 ww = *(const f32x4*)(w + c0);
;       f32x4 y;
;       if (MODE == 2) {
; #pragma unroll
;         for (int e = 0; e < 4; ++e) y[e] = v[i][e] * rstd * ww[e];
;         *(f32x4*)(p.out + (size_t)row * 1024 + c0) = y;
;       } else {
;         f32x4 sc = *(const f32x4*)(modl + (size_t)b * 6144 + sc_off + c0);
;         f32x4 sh = *(const f32x4*)(modl + (size_t)b * 6144 + sh_off + c0);
; #pragma unroll
;         for (int e = 0; e < 4; ++e) y[e] = v[i][e] * rstd * ww[e] * (1.f + sc[e]) + sh[e];
;         uint2 pk; pk.x = (unsigned)f2bf(y[0]) | ((unsigned)f2bf(y[1]) << 16); pk.y = (unsigned)f2bf(y[2]) | ((unsigned)f2bf(y[3]) << 16);
;         *(uint2*)(hn + a_off(row, c0, 32)) = pk;
	v_mov_b32_e32 v69, v28
	v_mov_b32_e32 v24, v23
	v_mov_b32_e32 v28, v27
	v_mov_b32_e32 v30, v22
	v_mov_b32_e32 v68, v26
	s_waitcnt vmcnt(1)
	v_mov_b32_e32 v71, v66
	v_mov_b32_e32 v66, v65
	v_pk_mul_f32 v[10:11], v[24:25], v[10:11]
	v_pk_add_f32 v[24:25], v[28:29], 1.0 op_sel_hi:[1,0]
	v_mov_b32_e32 v70, v64
	v_pk_mul_f32 v[14:15], v[30:31], v[14:15]
	v_pk_add_f32 v[22:23], v[68:69], 1.0 op_sel_hi:[1,0]
	v_pk_fma_f32 v[10:11], v[24:25], v[10:11], v[66:67]
	v_pk_fma_f32 v[14:15], v[22:23], v[14:15], v[70:71]
	v_and_b32_sdwa v23, v11, v86 dst_sel:DWORD dst_unused:UNUSED_PAD src0_sel:WORD_1 src1_sel:DWORD
	v_and_b32_sdwa v24, v10, v86 dst_sel:DWORD dst_unused:UNUSED_PAD src0_sel:WORD_1 src1_sel:DWORD
	v_and_b32_sdwa v13, v15, v86 dst_sel:DWORD dst_unused:UNUSED_PAD src0_sel:WORD_1 src1_sel:DWORD
	v_and_b32_sdwa v22, v14, v86 dst_sel:DWORD dst_unused:UNUSED_PAD src0_sel:WORD_1 src1_sel:DWORD
	v_add3_u32 v11, v11, v23, s19
	v_add3_u32 v10, v10, v24, s19
	v_add3_u32 v14, v14, v22, s19
	v_add3_u32 v13, v15, v13, s19
	v_and_b32_e32 v11, 0xffff0000, v11
	v_and_b32_e32 v10, 0xffff0000, v10
	v_or_b32_sdwa v11, v11, v13 dst_sel:DWORD dst_unused:UNUSED_PAD src0_sel:DWORD src1_sel:WORD_1
	v_or_b32_sdwa v10, v10, v14 dst_sel:DWORD dst_unused:UNUSED_PAD src0_sel:DWORD src1_sel:WORD_1
	v_mov_b32_e32 v250, v8
	v_mov_b32_e32 v251, v9
	v_mov_b32_e32 v252, v10
	v_mov_b32_e32 v253, v11
	global_load_dwordx4 v[8:11], v[42:43], off
	v_lshl_add_u64 v[14:15], v[16:17], 0, v[56:57]
	global_load_dwordx4 v[22:25], v[14:15], off
	global_load_dwordx4 v[26:29], v[18:19], off offset:2048
	global_store_dwordx2 v[250:251], v[252:253], off
	v_mov_b32_e32 v15, v6
	v_mov_b32_e32 v6, v5
	v_mov_b32_e32 v14, v4
	v_pk_mul_f32 v[6:7], v[6:7], v[12:13] op_sel_hi:[1,0]
	v_or_b32_e32 v4, v87, v81
	v_pk_mul_f32 v[14:15], v[14:15], v[12:13] op_sel_hi:[1,0]
	v_ashrrev_i32_e32 v5, 31, v4
	v_lshlrev_b64 v[4:5], 14, v[4:5]
	v_lshl_add_u64 v[4:5], s[62:63], 0, v[4:5]
	v_lshl_add_u64 v[4:5], v[4:5], 0, v[34:35]
	v_lshl_add_u64 v[4:5], v[4:5], 0, v[20:21]
	s_waitcnt vmcnt(3)
	v_mov_b32_e32 v31, v10
	s_waitcnt vmcnt(2)
	v_mov_b32_e32 v65, v24
	v_mov_b32_e32 v10, v9
	v_mov_b32_e32 v24, v23
	v_mov_b32_e32 v30, v8
	v_mov_b32_e32 v64, v22
	s_waitcnt vmcnt(1)
	v_mov_b32_e32 v67, v28
	v_mov_b32_e32 v28, v27
	v_pk_mul_f32 v[6:7], v[6:7], v[10:11]
	v_pk_add_f32 v[10:11], v[24:25], 1.0 op_sel_hi:[1,0]
	v_mov_b32_e32 v66, v26
	v_pk_mul_f32 v[8:9], v[14:15], v[30:31]
	v_pk_add_f32 v[14:15], v[64:65], 1.0 op_sel_hi:[1,0]
	v_pk_fma_f32 v[6:7], v[6:7], v[10:11], v[28:29]
	v_pk_fma_f32 v[8:9], v[8:9], v[14:15], v[66:67]
	v_and_b32_sdwa v13, v7, v86 dst_sel:DWORD dst_unused:UNUSED_PAD src0_sel:WORD_1 src1_sel:DWORD
	v_and_b32_sdwa v14, v6, v86 dst_sel:DWORD dst_unused:UNUSED_PAD src0_sel:WORD_1 src1_sel:DWORD
	v_and_b32_sdwa v10, v9, v86 dst_sel:DWORD dst_unused:UNUSED_PAD src0_sel:WORD_1 src1_sel:DWORD
	v_and_b32_sdwa v11, v8, v86 dst_sel:DWORD dst_unused:UNUSED_PAD src0_sel:WORD_1 src1_sel:DWORD
	v_add3_u32 v7, v7, v13, s19
	v_add3_u32 v6, v6, v14, s19
	v_add3_u32 v8, v8, v11, s19
	v_add3_u32 v9, v9, v10, s19
	v_and_b32_e32 v7, 0xffff0000, v7
	v_and_b32_e32 v6, 0xffff0000, v6
	v_or_b32_sdwa v7, v7, v9 dst_sel:DWORD dst_unused:UNUSED_PAD src0_sel:DWORD src1_sel:WORD_1
	v_or_b32_sdwa v6, v6, v8 dst_sel:DWORD dst_unused:UNUSED_PAD src0_sel:DWORD src1_sel:WORD_1
	v_mov_b32_e32 v250, v4
	v_mov_b32_e32 v251, v5
	v_mov_b32_e32 v252, v6
	v_mov_b32_e32 v253, v7
	global_load_dwordx4 v[4:7], v[44:45], off
	v_lshl_add_u64 v[22:23], v[16:17], 0, v[60:61]
	global_load_dwordx4 v[8:11], v[22:23], off
	global_load_dwordx4 v[14:17], v[18:19], off offset:3072
	global_store_dwordx2 v[250:251], v[252:253], off
	v_mov_b32_e32 v18, v0
	v_or_b32_e32 v0, v87, v82
	v_mov_b32_e32 v19, v2
	v_mov_b32_e32 v2, v1
	v_ashrrev_i32_e32 v1, 31, v0
	v_lshlrev_b64 v[0:1], 14, v[0:1]
	v_lshl_add_u64 v[0:1], s[62:63], 0, v[0:1]
	v_lshl_add_u64 v[0:1], v[0:1], 0, v[34:35]
	v_lshl_add_u64 v[0:1], v[0:1], 0, v[20:21]
	v_pk_mul_f32 v[18:19], v[18:19], v[12:13] op_sel_hi:[1,0]
	v_pk_mul_f32 v[2:3], v[2:3], v[12:13] op_sel_hi:[1,0]
	s_waitcnt vmcnt(3)
	v_mov_b32_e32 v13, v6
	s_waitcnt vmcnt(2)
	v_mov_b32_e32 v21, v10
	v_mov_b32_e32 v6, v5
	v_mov_b32_e32 v10, v9
	v_mov_b32_e32 v12, v4
	v_mov_b32_e32 v20, v8
	s_waitcnt vmcnt(1)
	v_mov_b32_e32 v23, v16
	v_mov_b32_e32 v16, v15
	v_pk_mul_f32 v[2:3], v[2:3], v[6:7]
	v_pk_add_f32 v[6:7], v[10:11], 1.0 op_sel_hi:[1,0]
	v_mov_b32_e32 v22, v14
	v_pk_mul_f32 v[4:5], v[18:19], v[12:13]
	v_pk_add_f32 v[8:9], v[20:21], 1.0 op_sel_hi:[1,0]
	v_pk_fma_f32 v[2:3], v[2:3], v[6:7], v[16:17]
	v_pk_fma_f32 v[4:5], v[4:5], v[8:9], v[22:23]
	v_and_b32_sdwa v8, v3, v86 dst_sel:DWORD dst_unused:UNUSED_PAD src0_sel:WORD_1 src1_sel:DWORD
	v_and_b32_sdwa v9, v2, v86 dst_sel:DWORD dst_unused:UNUSED_PAD src0_sel:WORD_1 src1_sel:DWORD
	v_and_b32_sdwa v6, v5, v86 dst_sel:DWORD dst_unused:UNUSED_PAD src0_sel:WORD_1 src1_sel:DWORD
	v_and_b32_sdwa v7, v4, v86 dst_sel:DWORD dst_unused:UNUSED_PAD src0_sel:WORD_1 src1_sel:DWORD
	v_add3_u32 v3, v3, v8, s19
	v_add3_u32 v2, v2, v9, s19
	v_add3_u32 v4, v4, v7, s19
	v_add3_u32 v5, v5, v6, s19
	v_and_b32_e32 v3, 0xffff0000, v3
	v_and_b32_e32 v2, 0xffff0000, v2
	v_or_b32_sdwa v3, v3, v5 dst_sel:DWORD dst_unused:UNUSED_PAD src0_sel:DWORD src1_sel:WORD_1
	v_or_b32_sdwa v2, v2, v4 dst_sel:DWORD dst_unused:UNUSED_PAD src0_sel:DWORD src1_sel:WORD_1
	global_store_dwordx2 v[0:1], v[2:3], off
	s_branch .LBB0_1637

; __device__ __forceinline__ u16 f2bf(float x) { unsigned u = __float_as_uint(x); u += 0x7fffu + ((u >> 16) & 1u); return (u16)(u >> 16); }
; __device__ __forceinline__ size_t a_off(int row, int col, int nks) { return ((size_t)((row >> 8) * nks + (col >> 5)) << 13) + ((row & 255) << 5) + swzc(row, col & 31); }
; template <int MODE>
; __device__ __forceinline__ void norm_phase(const Params& p, const float* src, const float* w, const float* modl, int sh_off, int sc_off,
;                            char* smem, int bid, int nblk) {
;     ...
;     float ss = 0.f;
; #pragma unroll
;     for (int i = 0; i < 4; ++i) ss += v[i][0] * v[i][0] + v[i][1] * v[i][1] + v[i][2] * v[i][2] + v[i][3] * v[i][3];
; #pragma unroll
;     for (int o = 32; o >= 1; o >>= 1) ss += __shfl_xor(ss, o);
;     const float rstd = rsqrtf(ss * (1.f / 1024.f) + 1e-6f);
;     const int b = row >> 13;
;     float dots[8];
;     if (MODE == 1) { for (int j = 0; j < 8; ++j) dots[j] = 0.f; }
; #pragma unroll
;     for (int i = 0; i < 4; ++i) {
;       const int c0 = i * 256 + lane * 4;
;       f32x4 ww = *(const f32x4*)(w + c0);
;       f32x4 y;
;       if (MODE == 2) {
; #pragma unroll
;         for (int e = 0; e < 4; ++e) y[e] = v[i][e] * rstd * ww[e];
;         *(f32x4*)(p.out + (size_t)row * 1024 + c0) = y;
;       } else {
;         f32x4 sc = *(const f32x4*)(modl + (size_t)b * 6144 + sc_off + c0);
;         f32x4 sh = *(const f32x4*)(modl + (size_t)b * 6144 + sh_off + c0);
; #pragma unroll
;         for (int e = 0; e < 4; ++e) y[e] = v[i][e] * rstd * ww[e] * (1.f + sc[e]) + sh[e];
;         uint2 pk; pk.x = (unsigned)f2bf(y[0]) | ((unsigned)f2bf(y[1]) << 16); pk.y = (unsigned)f2bf(y[2]) | ((unsigned)f2bf(y[3]) << 16);
;         *(uint2*)(hn + a_off(row, c0, 32)) = pk;
.LBB0_1945:
	s_or_b64 exec, exec, s[0:1]
	v_ashrrev_i32_e32 v34, 13, v33
	v_mul_i32_i24_e32 v66, 0x1800, v34
	v_ashrrev_i32_e32 v67, 31, v66
	v_lshl_add_u64 v[68:69], v[66:67], 2, s[6:7]
	v_lshl_add_u64 v[66:67], v[68:69], 0, s[14:15]
	global_load_dwordx4 v[88:91], v[38:39], off
	v_lshl_add_u64 v[92:93], v[66:67], 0, v[50:51]
	v_lshl_add_u64 v[68:69], v[68:69], 0, s[16:17]
	global_load_dwordx4 v[92:95], v[92:93], off
	v_lshl_add_u64 v[96:97], v[68:69], 0, v[50:51]
	global_load_dwordx4 v[96:99], v[96:97], off
	s_waitcnt vmcnt(0)
	v_pk_mul_f32 v[102:103], v[28:29], v[28:29]
	v_pk_mul_f32 v[104:105], v[24:25], v[24:25]
	v_pk_mul_f32 v[70:71], v[30:31], v[30:31]
	v_pk_mul_f32 v[100:101], v[26:27], v[26:27]
	v_mov_b32_e32 v106, v102
	v_mov_b32_e32 v107, v104
	v_mov_b32_e32 v104, v103
	v_pk_add_f32 v[102:103], v[106:107], v[104:105]
	v_mov_b32_e32 v104, v70
	v_mov_b32_e32 v105, v100
	v_pk_add_f32 v[102:103], v[104:105], v[102:103]
	v_mov_b32_e32 v100, v71
	v_pk_add_f32 v[70:71], v[100:101], v[102:103]
	v_mov_b32_e32 v102, v17
	v_mov_b32_e32 v103, v21
	v_mov_b32_e32 v100, v16
	v_mov_b32_e32 v101, v20
	v_pk_mul_f32 v[102:103], v[102:103], v[102:103]
	v_add_f32_e32 v34, v70, v71
	v_pk_fma_f32 v[100:101], v[100:101], v[100:101], v[102:103]
	v_mov_b32_e32 v102, v18
	v_mov_b32_e32 v103, v22
	v_pk_fma_f32 v[100:101], v[102:103], v[102:103], v[100:101]
	v_mov_b32_e32 v102, v19
	v_mov_b32_e32 v103, v23
	v_pk_fma_f32 v[100:101], v[102:103], v[102:103], v[100:101]
	v_and_b32_e32 v61, 24, v83
	v_add_f32_e32 v34, v101, v34
	v_add_f32_e32 v34, v100, v34
	s_nop 1
	v_mov_b32_e32 v49, v34
	s_nop 1
	v_permlane32_swap_b32_e32 v34, v49
	v_mov_b32_e32 v101, v30
	v_mov_b32_e32 v30, v29
	v_and_b32_e32 v57, 0x1fe0, v84
	v_sub_u32_e32 v61, 0, v61
	s_waitcnt lgkmcnt(0)
	v_add_f32_e32 v34, v34, v49
	s_nop 1
	v_mov_b32_e32 v49, v34
	s_nop 1
	v_permlane16_swap_b32_e32 v34, v49
	v_mov_b32_e32 v100, v28
	v_ashrrev_i32_e32 v53, 3, v33
	v_and_b32_e32 v53, 0xffffffe0, v53
	v_or_b32_e32 v28, v53, v78
	s_waitcnt lgkmcnt(0)
	v_add_f32_e32 v34, v34, v49
	s_nop 1
	v_mov_b32_dpp v49, v34 row_ror:8 row_mask:0xf bank_mask:0xf
	v_mov_b32_e32 v71, v35
	s_waitcnt lgkmcnt(0)
	v_add_f32_e32 v34, v34, v49
	s_nop 1
	v_mov_b32_dpp v49, v34 row_ror:4 row_mask:0xf bank_mask:0xf
	s_waitcnt lgkmcnt(0)
	v_add_f32_e32 v29, v34, v49
	s_nop 1
	v_mov_b32_dpp v49, v29 quad_perm:[2,3,0,1] row_mask:0xf bank_mask:0xf
	v_lshlrev_b32_e32 v34, 1, v57
	v_xor_b32_e32 v57, v32, v61
	v_and_or_b32 v57, v57, 24, v79
	v_lshlrev_b32_e32 v70, 1, v57
	s_waitcnt lgkmcnt(0)
	v_add_f32_e32 v49, v29, v49
	s_nop 1
	v_mov_b32_dpp v61, v49 quad_perm:[1,0,3,2] row_mask:0xf bank_mask:0xf
	v_ashrrev_i32_e32 v29, 31, v28
	v_lshlrev_b64 v[28:29], 14, v[28:29]
	v_lshl_add_u64 v[28:29], s[62:63], 0, v[28:29]
	v_lshl_add_u64 v[28:29], v[28:29], 0, v[34:35]
	s_waitcnt lgkmcnt(0)
	v_add_f32_e32 v49, v49, v61
	v_fmamk_f32 v49, v49, 0x3a800000, v85
	v_mul_f32_e32 v57, 0x4b800000, v49
	v_cmp_gt_f32_e64 s[0:1], s20, v49
	v_lshl_add_u64 v[28:29], v[28:29], 0, v[70:71]
	v_mov_b32_e32 v104, v88
	v_cndmask_b32_e64 v49, v49, v57, s[0:1]
	v_rsq_f32_e32 v49, v49
	v_mov_b32_e32 v105, v90
	v_mov_b32_e32 v90, v89
	v_mul_f32_e32 v57, 0x45800000, v49
	v_cndmask_b32_e64 v102, v49, v57, s[0:1]
	v_pk_mul_f32 v[100:101], v[100:101], v[102:103] op_sel_hi:[1,0]
	v_pk_mul_f32 v[30:31], v[30:31], v[102:103] op_sel_hi:[1,0]
	v_pk_mul_f32 v[88:89], v[104:105], v[100:101]
	v_mov_b32_e32 v101, v94
	v_mov_b32_e32 v94, v93
	v_mov_b32_e32 v100, v92
	v_mov_b32_e32 v105, v98
	v_pk_mul_f32 v[30:31], v[90:91], v[30:31]
	v_pk_add_f32 v[90:91], v[94:95], 1.0 op_sel_hi:[1,0]
	v_mov_b32_e32 v98, v97
	v_mov_b32_e32 v104, v96
	v_pk_add_f32 v[100:101], v[100:101], 1.0 op_sel_hi:[1,0]
	v_pk_fma_f32 v[30:31], v[90:91], v[30:31], v[98:99]
	v_pk_fma_f32 v[88:89], v[100:101], v[88:89], v[104:105]
	v_and_b32_sdwa v61, v31, v86 dst_sel:DWORD dst_unused:UNUSED_PAD src0_sel:WORD_1 src1_sel:DWORD
	v_and_b32_sdwa v65, v30, v86 dst_sel:DWORD dst_unused:UNUSED_PAD src0_sel:WORD_1 src1_sel:DWORD
	v_and_b32_sdwa v49, v89, v86 dst_sel:DWORD dst_unused:UNUSED_PAD src0_sel:WORD_1 src1_sel:DWORD
	v_and_b32_sdwa v57, v88, v86 dst_sel:DWORD dst_unused:UNUSED_PAD src0_sel:WORD_1 src1_sel:DWORD
	v_add3_u32 v31, v31, v61, s21
	v_add3_u32 v30, v30, v65, s21
	v_add3_u32 v57, v88, v57, s21
	v_add3_u32 v49, v89, v49, s21
	v_and_b32_e32 v31, 0xffff0000, v31
	v_and_b32_e32 v30, 0xffff0000, v30
	v_or_b32_sdwa v31, v31, v49 dst_sel:DWORD dst_unused:UNUSED_PAD src0_sel:DWORD src1_sel:WORD_1
	v_or_b32_sdwa v30, v30, v57 dst_sel:DWORD dst_unused:UNUSED_PAD src0_sel:DWORD src1_sel:WORD_1
	v_mov_b32_e32 v250, v28
	v_mov_b32_e32 v251, v29
	v_mov_b32_e32 v252, v30
	v_mov_b32_e32 v253, v31
	v_lshl_add_u64 v[88:89], v[66:67], 0, v[54:55]
	global_load_dwordx4 v[28:31], v[40:41], off
	v_lshl_add_u64 v[92:93], v[68:69], 0, v[54:55]
	global_load_dwordx4 v[88:91], v[88:89], off
	v_mov_b32_e32 v97, v26
	global_load_dwordx4 v[92:95], v[92:93], off
	global_store_dwordx2 v[250:251], v[252:253], off
	v_mov_b32_e32 v26, v25
	v_mov_b32_e32 v96, v24
	v_pk_mul_f32 v[26:27], v[26:27], v[102:103] op_sel_hi:[1,0]
	v_or_b32_e32 v24, v53, v80
	v_pk_mul_f32 v[96:97], v[96:97], v[102:103] op_sel_hi:[1,0]
	v_ashrrev_i32_e32 v25, 31, v24
	v_lshlrev_b64 v[24:25], 14, v[24:25]
	v_lshl_add_u64 v[24:25], s[62:63], 0, v[24:25]
	v_lshl_add_u64 v[24:25], v[24:25], 0, v[34:35]
	v_lshl_add_u64 v[24:25], v[24:25], 0, v[70:71]
	s_waitcnt vmcnt(3)
	v_mov_b32_e32 v99, v30
	v_mov_b32_e32 v30, v29
	s_waitcnt vmcnt(2)
	v_mov_b32_e32 v101, v90
	v_mov_b32_e32 v90, v89
	v_mov_b32_e32 v98, v28
	v_mov_b32_e32 v100, v88
	s_waitcnt vmcnt(1)
; __device__ __forceinline__ u16 f2bf(float x) { unsigned u = __float_as_uint(x); u += 0x7fffu + ((u >> 16) & 1u); return (u16)(u >> 16); }
; __device__ __forceinline__ size_t a_off(int row, int col, int nks) { return ((size_t)((row >> 8) * nks + (col >> 5)) << 13) + ((row & 255) << 5) + swzc(row, col & 31); }
; template <int MODE>
; __device__ __forceinline__ void norm_phase(const Params& p, const float* src, const float* w, const float* modl, int sh_off, int sc_off,
;                            char* smem, int bid, int nblk) {
;     ...
;       f32x4 ww = *(const f32x4*)(w + c0);
;       f32x4 y;
;       if (MODE == 2) {
; #pragma unroll
;         for (int e = 0; e < 4; ++e) y[e] = v[i][e] * rstd * ww[e];
;         *(f32x4*)(p.out + (size_t)row * 1024 + c0) = y;
;       } else {
;         f32x4 sc = *(const f32x4*)(modl + (size_t)b * 6144 + sc_off + c0);
;         f32x4 sh = *(const f32x4*)(modl + (size_t)b * 6144 + sh_off + c0);
; #pragma unroll
;         for (int e = 0; e < 4; ++e) y[e] = v[i][e] * rstd * ww[e] * (1.f + sc[e]) + sh[e];
;         uint2 pk; pk.x = (unsigned)f2bf(y[0]) | ((unsigned)f2bf(y[1]) << 16); pk.y = (unsigned)f2bf(y[2]) | ((unsigned)f2bf(y[3]) << 16);
;         *(uint2*)(hn + a_off(row, c0, 32)) = pk;
	v_mov_b32_e32 v105, v94
	v_mov_b32_e32 v94, v93
	v_pk_mul_f32 v[26:27], v[30:31], v[26:27]
	v_pk_add_f32 v[30:31], v[90:91], 1.0 op_sel_hi:[1,0]
	v_mov_b32_e32 v104, v92
	v_pk_mul_f32 v[28:29], v[98:99], v[96:97]
	v_pk_add_f32 v[88:89], v[100:101], 1.0 op_sel_hi:[1,0]
	v_pk_fma_f32 v[26:27], v[30:31], v[26:27], v[94:95]
	v_pk_fma_f32 v[28:29], v[88:89], v[28:29], v[104:105]
	v_and_b32_sdwa v49, v27, v86 dst_sel:DWORD dst_unused:UNUSED_PAD src0_sel:WORD_1 src1_sel:DWORD
	v_and_b32_sdwa v57, v26, v86 dst_sel:DWORD dst_unused:UNUSED_PAD src0_sel:WORD_1 src1_sel:DWORD
	v_and_b32_sdwa v30, v29, v86 dst_sel:DWORD dst_unused:UNUSED_PAD src0_sel:WORD_1 src1_sel:DWORD
	v_and_b32_sdwa v31, v28, v86 dst_sel:DWORD dst_unused:UNUSED_PAD src0_sel:WORD_1 src1_sel:DWORD
	v_add3_u32 v27, v27, v49, s21
	v_add3_u32 v26, v26, v57, s21
	v_add3_u32 v28, v28, v31, s21
	v_add3_u32 v29, v29, v30, s21
	v_and_b32_e32 v27, 0xffff0000, v27
	v_and_b32_e32 v26, 0xffff0000, v26
	v_or_b32_sdwa v27, v27, v29 dst_sel:DWORD dst_unused:UNUSED_PAD src0_sel:DWORD src1_sel:WORD_1
	v_or_b32_sdwa v26, v26, v28 dst_sel:DWORD dst_unused:UNUSED_PAD src0_sel:DWORD src1_sel:WORD_1
	v_mov_b32_e32 v250, v24
	v_mov_b32_e32 v251, v25
	v_mov_b32_e32 v252, v26
	v_mov_b32_e32 v253, v27
	v_lshl_add_u64 v[28:29], v[66:67], 0, v[58:59]
	global_load_dwordx4 v[24:27], v[42:43], off
	v_lshl_add_u64 v[88:89], v[68:69], 0, v[58:59]
	global_load_dwordx4 v[28:31], v[28:29], off
	v_mov_b32_e32 v93, v22
	global_load_dwordx4 v[88:91], v[88:89], off
	global_store_dwordx2 v[250:251], v[252:253], off
	v_mov_b32_e32 v22, v21
	v_mov_b32_e32 v92, v20
	v_pk_mul_f32 v[22:23], v[22:23], v[102:103] op_sel_hi:[1,0]
	v_or_b32_e32 v20, v53, v81
	v_pk_mul_f32 v[92:93], v[92:93], v[102:103] op_sel_hi:[1,0]
	v_ashrrev_i32_e32 v21, 31, v20
	v_lshlrev_b64 v[20:21], 14, v[20:21]
	v_lshl_add_u64 v[20:21], s[62:63], 0, v[20:21]
	v_lshl_add_u64 v[20:21], v[20:21], 0, v[34:35]
	v_lshl_add_u64 v[20:21], v[20:21], 0, v[70:71]
	s_waitcnt vmcnt(3)
	v_mov_b32_e32 v95, v26
	v_mov_b32_e32 v26, v25
	s_waitcnt vmcnt(2)
	v_mov_b32_e32 v97, v30
	v_mov_b32_e32 v30, v29
	v_mov_b32_e32 v94, v24
	v_mov_b32_e32 v96, v28
	s_waitcnt vmcnt(1)
	v_mov_b32_e32 v99, v90
	v_mov_b32_e32 v90, v89
	v_pk_mul_f32 v[22:23], v[22:23], v[26:27]
	v_pk_add_f32 v[26:27], v[30:31], 1.0 op_sel_hi:[1,0]
	v_mov_b32_e32 v98, v88
	v_pk_mul_f32 v[24:25], v[92:93], v[94:95]
	v_pk_add_f32 v[28:29], v[96:97], 1.0 op_sel_hi:[1,0]
	v_pk_fma_f32 v[22:23], v[22:23], v[26:27], v[90:91]
	v_pk_fma_f32 v[24:25], v[24:25], v[28:29], v[98:99]
	v_and_b32_sdwa v28, v23, v86 dst_sel:DWORD dst_unused:UNUSED_PAD src0_sel:WORD_1 src1_sel:DWORD
	v_and_b32_sdwa v29, v22, v86 dst_sel:DWORD dst_unused:UNUSED_PAD src0_sel:WORD_1 src1_sel:DWORD
	v_and_b32_sdwa v26, v25, v86 dst_sel:DWORD dst_unused:UNUSED_PAD src0_sel:WORD_1 src1_sel:DWORD
	v_and_b32_sdwa v27, v24, v86 dst_sel:DWORD dst_unused:UNUSED_PAD src0_sel:WORD_1 src1_sel:DWORD
	v_add3_u32 v23, v23, v28, s21
	v_add3_u32 v22, v22, v29, s21
	v_add3_u32 v24, v24, v27, s21
	v_add3_u32 v25, v25, v26, s21
	v_and_b32_e32 v23, 0xffff0000, v23
	v_and_b32_e32 v22, 0xffff0000, v22
	v_or_b32_sdwa v23, v23, v25 dst_sel:DWORD dst_unused:UNUSED_PAD src0_sel:DWORD src1_sel:WORD_1
	v_or_b32_sdwa v22, v22, v24 dst_sel:DWORD dst_unused:UNUSED_PAD src0_sel:DWORD src1_sel:WORD_1
	v_mov_b32_e32 v250, v20
	v_mov_b32_e32 v251, v21
	v_mov_b32_e32 v252, v22
	v_mov_b32_e32 v253, v23
	v_lshl_add_u64 v[24:25], v[66:67], 0, v[62:63]
	global_load_dwordx4 v[20:23], v[44:45], off
	v_lshl_add_u64 v[28:29], v[68:69], 0, v[62:63]
	global_load_dwordx4 v[24:27], v[24:25], off
	v_mov_b32_e32 v66, v16
	global_load_dwordx4 v[28:31], v[28:29], off
	global_store_dwordx2 v[250:251], v[252:253], off
	v_or_b32_e32 v16, v53, v82
	v_mov_b32_e32 v67, v18
	v_mov_b32_e32 v18, v17
	v_ashrrev_i32_e32 v17, 31, v16
	v_lshlrev_b64 v[16:17], 14, v[16:17]
	v_lshl_add_u64 v[16:17], s[62:63], 0, v[16:17]
	v_lshl_add_u64 v[16:17], v[16:17], 0, v[34:35]
	v_lshl_add_u64 v[16:17], v[16:17], 0, v[70:71]
	v_pk_mul_f32 v[18:19], v[18:19], v[102:103] op_sel_hi:[1,0]
	v_pk_mul_f32 v[66:67], v[66:67], v[102:103] op_sel_hi:[1,0]
	s_waitcnt vmcnt(3)
	v_mov_b32_e32 v69, v22
	v_mov_b32_e32 v22, v21
	s_waitcnt vmcnt(2)
	v_mov_b32_e32 v71, v26
	v_mov_b32_e32 v26, v25
	v_mov_b32_e32 v68, v20
	v_mov_b32_e32 v70, v24
	s_waitcnt vmcnt(1)
	v_mov_b32_e32 v89, v30
	v_mov_b32_e32 v30, v29
	v_pk_mul_f32 v[18:19], v[18:19], v[22:23]
	v_pk_add_f32 v[22:23], v[26:27], 1.0 op_sel_hi:[1,0]
	v_mov_b32_e32 v88, v28
	v_pk_mul_f32 v[20:21], v[66:67], v[68:69]
	v_pk_add_f32 v[24:25], v[70:71], 1.0 op_sel_hi:[1,0]
	v_pk_fma_f32 v[18:19], v[18:19], v[22:23], v[30:31]
	v_pk_fma_f32 v[20:21], v[20:21], v[24:25], v[88:89]
	v_and_b32_sdwa v24, v19, v86 dst_sel:DWORD dst_unused:UNUSED_PAD src0_sel:WORD_1 src1_sel:DWORD
	v_and_b32_sdwa v25, v18, v86 dst_sel:DWORD dst_unused:UNUSED_PAD src0_sel:WORD_1 src1_sel:DWORD
	v_and_b32_sdwa v22, v21, v86 dst_sel:DWORD dst_unused:UNUSED_PAD src0_sel:WORD_1 src1_sel:DWORD
	v_and_b32_sdwa v23, v20, v86 dst_sel:DWORD dst_unused:UNUSED_PAD src0_sel:WORD_1 src1_sel:DWORD
	v_add3_u32 v19, v19, v24, s21
	v_add3_u32 v18, v18, v25, s21
	v_add3_u32 v20, v20, v23, s21
	v_add3_u32 v21, v21, v22, s21
	v_and_b32_e32 v19, 0xffff0000, v19
	v_and_b32_e32 v18, 0xffff0000, v18
	v_or_b32_sdwa v19, v19, v21 dst_sel:DWORD dst_unused:UNUSED_PAD src0_sel:DWORD src1_sel:WORD_1
	v_or_b32_sdwa v18, v18, v20 dst_sel:DWORD dst_unused:UNUSED_PAD src0_sel:DWORD src1_sel:WORD_1
	global_store_dwordx2 v[16:17], v[18:19], off
	s_and_saveexec_b64 s[0:1], vcc
	s_cbranch_execz .LBB0_1936
; __device__ __forceinline__ u16 f2bf(float x) { unsigned u = __float_as_uint(x); u += 0x7fffu + ((u >> 16) & 1u); return (u16)(u >> 16); }
; __device__ __forceinline__ size_t a_off(int row, int col, int nks) { return ((size_t)((row >> 8) * nks + (col >> 5)) << 13) + ((row & 255) << 5) + swzc(row, col & 31); }
; template <int MODE>
; __device__ __forceinline__ void norm_phase(const Params& p, const float* src, const float* w, const float* modl, int sh_off, int sc_off,
;                            char* smem, int bid, int nblk) {
;     ...
;     float ss = 0.f;
; #pragma unroll
;     for (int i = 0; i < 4; ++i) ss += v[i][0] * v[i][0] + v[i][1] * v[i][1] + v[i][2] * v[i][2] + v[i][3] * v[i][3];
; #pragma unroll
;     for (int o = 32; o >= 1; o >>= 1) ss += __shfl_xor(ss, o);
;     const float rstd = rsqrtf(ss * (1.f / 1024.f) + 1e-6f);
;     const int b = row >> 13;
;     float dots[8];
;     if (MODE == 1) { for (int j = 0; j < 8; ++j) dots[j] = 0.f; }
; #pragma unroll
;     for (int i = 0; i < 4; ++i) {
;       const int c0 = i * 256 + lane * 4;
;       f32x4 ww = *(const f32x4*)(w + c0);
;       f32x4 y;
;       if (MODE == 2) {
; #pragma unroll
;         for (int e = 0; e < 4; ++e) y[e] = v[i][e] * rstd * ww[e];
;         *(f32x4*)(p.out + (size_t)row * 1024 + c0) = y;
;       } else {
;         f32x4 sc = *(const f32x4*)(modl + (size_t)b * 6144 + sc_off + c0);
;         f32x4 sh = *(const f32x4*)(modl + (size_t)b * 6144 + sh_off + c0);
; #pragma unroll
;         for (int e = 0; e < 4; ++e) y[e] = v[i][e] * rstd * ww[e] * (1.f + sc[e]) + sh[e];
;         uint2 pk; pk.x = (unsigned)f2bf(y[0]) | ((unsigned)f2bf(y[1]) << 16); pk.y = (unsigned)f2bf(y[2]) | ((unsigned)f2bf(y[3]) << 16);
;         *(uint2*)(hn + a_off(row, c0, 32)) = pk;
	v_ashrrev_i32_e32 v16, 13, v64
	v_mul_i32_i24_e32 v16, 0x1800, v16
	v_ashrrev_i32_e32 v17, 31, v16
	v_lshl_add_u64 v[18:19], v[16:17], 2, s[6:7]
	v_lshl_add_u64 v[16:17], v[18:19], 0, s[14:15]
	v_mov_b32_e32 v49, v35
	global_load_dwordx4 v[22:25], v[38:39], off
	v_lshl_add_u64 v[26:27], v[16:17], 0, v[48:49]
	v_lshl_add_u64 v[18:19], v[18:19], 0, s[16:17]
	global_load_dwordx4 v[26:29], v[26:27], off
	v_lshl_add_u64 v[30:31], v[18:19], 0, v[48:49]
	global_load_dwordx4 v[66:69], v[30:31], off
	v_pk_mul_f32 v[70:71], v[8:9], v[8:9]
	v_pk_mul_f32 v[88:89], v[12:13], v[12:13]
	v_pk_mul_f32 v[20:21], v[14:15], v[14:15]
	v_pk_mul_f32 v[30:31], v[10:11], v[10:11]
	v_mov_b32_e32 v90, v88
	v_mov_b32_e32 v91, v70
	v_mov_b32_e32 v70, v89
	v_pk_add_f32 v[70:71], v[90:91], v[70:71]
	v_mov_b32_e32 v88, v20
	v_mov_b32_e32 v89, v30
	v_pk_add_f32 v[70:71], v[88:89], v[70:71]
	v_mov_b32_e32 v30, v21
	v_pk_add_f32 v[20:21], v[30:31], v[70:71]
	v_mov_b32_e32 v70, v5
	v_mov_b32_e32 v71, v1
	v_mov_b32_e32 v30, v4
	v_mov_b32_e32 v31, v0
	v_pk_mul_f32 v[70:71], v[70:71], v[70:71]
	v_add_f32_e32 v20, v20, v21
	v_pk_fma_f32 v[30:31], v[30:31], v[30:31], v[70:71]
	v_mov_b32_e32 v70, v6
	v_mov_b32_e32 v71, v2
	v_pk_fma_f32 v[30:31], v[70:71], v[70:71], v[30:31]
	v_mov_b32_e32 v70, v7
	v_mov_b32_e32 v71, v3
	v_pk_fma_f32 v[30:31], v[70:71], v[70:71], v[30:31]
	v_ashrrev_i32_e32 v34, 3, v64
	v_add_f32_e32 v20, v30, v20
	v_add_f32_e32 v20, v20, v31
	s_nop 1
	v_mov_b32_e32 v21, v20
	s_nop 1
	v_permlane32_swap_b32_e32 v20, v21
	v_mov_b32_e32 v30, v12
	v_add_u32_e32 v49, s9, v84
	v_add_u32_e32 v53, s8, v83
	v_and_b32_e32 v87, 0xffffffe0, v34
	s_waitcnt lgkmcnt(0)
	v_add_f32_e32 v20, v20, v21
	s_nop 1
	v_mov_b32_e32 v21, v20
	s_nop 1
	v_permlane16_swap_b32_e32 v20, v21
	v_and_b32_e32 v34, 24, v53
	v_or_b32_e32 v64, v87, v78
	v_ashrrev_i32_e32 v65, 31, v64
	v_lshlrev_b64 v[64:65], 14, v[64:65]
	s_waitcnt lgkmcnt(0)
	v_add_f32_e32 v20, v20, v21
	s_nop 1
	v_mov_b32_dpp v31, v20 row_ror:8 row_mask:0xf bank_mask:0xf
	v_lshl_add_u64 v[64:65], s[62:63], 0, v[64:65]
	v_mov_b32_e32 v21, v35
	v_mov_b32_e32 v53, v35
	v_mov_b32_e32 v57, v35
	s_waitcnt lgkmcnt(0)
	v_add_f32_e32 v12, v20, v31
	s_nop 1
	v_mov_b32_dpp v20, v12 row_ror:4 row_mask:0xf bank_mask:0xf
	v_mov_b32_e32 v31, v14
	v_and_b32_e32 v14, 0x1fe0, v49
	v_sub_u32_e32 v49, 0, v34
	v_lshlrev_b32_e32 v34, 1, v14
	s_waitcnt lgkmcnt(0)
	v_add_f32_e32 v12, v12, v20
	s_nop 1
	v_mov_b32_dpp v20, v12 quad_perm:[2,3,0,1] row_mask:0xf bank_mask:0xf
	v_lshl_add_u64 v[64:65], v[64:65], 0, v[34:35]
	v_mov_b32_e32 v61, v35
	s_waitcnt lgkmcnt(0)
	v_add_f32_e32 v12, v12, v20
	s_nop 1
	v_mov_b32_dpp v14, v12 quad_perm:[1,0,3,2] row_mask:0xf bank_mask:0xf
	v_xor_b32_e32 v20, v32, v49
	v_and_or_b32 v20, v20, 24, v79
	v_lshlrev_b32_e32 v20, 1, v20
	v_lshl_add_u64 v[64:65], v[64:65], 0, v[20:21]
	s_waitcnt lgkmcnt(0)
	v_add_f32_e32 v12, v12, v14
	v_fmamk_f32 v12, v12, 0x3a800000, v85
	v_mul_f32_e32 v14, 0x4b800000, v12
	v_cmp_gt_f32_e32 vcc, s20, v12
	s_waitcnt vmcnt(2)
	v_mov_b32_e32 v70, v22
	v_cndmask_b32_e32 v12, v12, v14, vcc
	v_rsq_f32_e32 v12, v12
	v_mov_b32_e32 v71, v24
	v_mov_b32_e32 v24, v23
	s_waitcnt vmcnt(0)
	v_mov_b32_e32 v89, v68
	v_mul_f32_e32 v14, 0x45800000, v12
	v_cndmask_b32_e32 v12, v12, v14, vcc
	v_pk_mul_f32 v[30:31], v[30:31], v[12:13] op_sel_hi:[1,0]
	v_mov_b32_e32 v14, v13
	v_pk_mul_f32 v[30:31], v[70:71], v[30:31]
	v_mov_b32_e32 v71, v28
	v_pk_mul_f32 v[14:15], v[14:15], v[12:13] op_sel_hi:[1,0]
	v_mov_b32_e32 v28, v27
	v_mov_b32_e32 v70, v26
	v_pk_mul_f32 v[14:15], v[24:25], v[14:15]
	v_pk_add_f32 v[22:23], v[28:29], 1.0 op_sel_hi:[1,0]
	v_mov_b32_e32 v68, v67
	v_mov_b32_e32 v88, v66
	v_pk_add_f32 v[70:71], v[70:71], 1.0 op_sel_hi:[1,0]
	v_pk_fma_f32 v[14:15], v[22:23], v[14:15], v[68:69]
	v_pk_fma_f32 v[30:31], v[70:71], v[30:31], v[88:89]
	v_and_b32_sdwa v23, v15, v86 dst_sel:DWORD dst_unused:UNUSED_PAD src0_sel:WORD_1 src1_sel:DWORD
	v_and_b32_sdwa v24, v14, v86 dst_sel:DWORD dst_unused:UNUSED_PAD src0_sel:WORD_1 src1_sel:DWORD
	v_and_b32_sdwa v13, v31, v86 dst_sel:DWORD dst_unused:UNUSED_PAD src0_sel:WORD_1 src1_sel:DWORD
	v_and_b32_sdwa v22, v30, v86 dst_sel:DWORD dst_unused:UNUSED_PAD src0_sel:WORD_1 src1_sel:DWORD
	v_add3_u32 v15, v15, v23, s21
	v_add3_u32 v14, v14, v24, s21
	v_add3_u32 v22, v30, v22, s21
	v_add3_u32 v13, v31, v13, s21
	v_and_b32_e32 v15, 0xffff0000, v15
	v_and_b32_e32 v14, 0xffff0000, v14
	v_or_b32_sdwa v15, v15, v13 dst_sel:DWORD dst_unused:UNUSED_PAD src0_sel:DWORD src1_sel:WORD_1
	v_or_b32_sdwa v14, v14, v22 dst_sel:DWORD dst_unused:UNUSED_PAD src0_sel:DWORD src1_sel:WORD_1
	v_mov_b32_e32 v250, v64
	v_mov_b32_e32 v251, v65
	v_mov_b32_e32 v252, v14
	v_mov_b32_e32 v253, v15
	v_lshl_add_u64 v[14:15], v[16:17], 0, v[52:53]
	global_load_dwordx4 v[22:25], v[40:41], off
	global_load_dwordx4 v[26:29], v[14:15], off
	v_lshl_add_u64 v[14:15], v[18:19], 0, v[52:53]
	global_load_dwordx4 v[64:67], v[14:15], off
	global_store_dwordx2 v[250:251], v[252:253], off
	v_mov_b32_e32 v15, v10
	v_mov_b32_e32 v10, v9
	v_mov_b32_e32 v14, v8
	v_pk_mul_f32 v[10:11], v[10:11], v[12:13] op_sel_hi:[1,0]
	v_or_b32_e32 v8, v87, v80
	v_pk_mul_f32 v[14:15], v[14:15], v[12:13] op_sel_hi:[1,0]
	v_ashrrev_i32_e32 v9, 31, v8
	v_lshlrev_b64 v[8:9], 14, v[8:9]
	v_lshl_add_u64 v[8:9], s[62:63], 0, v[8:9]
	v_lshl_add_u64 v[8:9], v[8:9], 0, v[34:35]
	v_lshl_add_u64 v[8:9], v[8:9], 0, v[20:21]
	s_waitcnt vmcnt(3)
	v_mov_b32_e32 v31, v24
	s_waitcnt vmcnt(2)
; __device__ __forceinline__ u16 f2bf(float x) { unsigned u = __float_as_uint(x); u += 0x7fffu + ((u >> 16) & 1u); return (u16)(u >> 16); }
; __device__ __forceinline__ size_t a_off(int row, int col, int nks) { return ((size_t)((row >> 8) * nks + (col >> 5)) << 13) + ((row & 255) << 5) + swzc(row, col & 31); }
; template <int MODE>
; __device__ __forceinline__ void norm_phase(const Params& p, const float* src, const float* w, const float* modl, int sh_off, int sc_off,
;                            char* smem, int bid, int nblk) {
;     ...
;       f32x4 ww = *(const f32x4*)(w + c0);
;       f32x4 y;
;       if (MODE == 2) {
; #pragma unroll
;         for (int e = 0; e < 4; ++e) y[e] = v[i][e] * rstd * ww[e];
;         *(f32x4*)(p.out + (size_t)row * 1024 + c0) = y;
;       } else {
;         f32x4 sc = *(const f32x4*)(modl + (size_t)b * 6144 + sc_off + c0);
;         f32x4 sh = *(const f32x4*)(modl + (size_t)b * 6144 + sh_off + c0);
; #pragma unroll
;         for (int e = 0; e < 4; ++e) y[e] = v[i][e] * rstd * ww[e] * (1.f + sc[e]) + sh[e];
;         uint2 pk; pk.x = (unsigned)f2bf(y[0]) | ((unsigned)f2bf(y[1]) << 16); pk.y = (unsigned)f2bf(y[2]) | ((unsigned)f2bf(y[3]) << 16);
;         *(uint2*)(hn + a_off(row, c0, 32)) = pk;
	v_mov_b32_e32 v69, v28
	v_mov_b32_e32 v24, v23
	v_mov_b32_e32 v28, v27
	v_mov_b32_e32 v30, v22
	v_mov_b32_e32 v68, v26
	s_waitcnt vmcnt(1)
	v_mov_b32_e32 v71, v66
	v_mov_b32_e32 v66, v65
	v_pk_mul_f32 v[10:11], v[24:25], v[10:11]
	v_pk_add_f32 v[24:25], v[28:29], 1.0 op_sel_hi:[1,0]
	v_mov_b32_e32 v70, v64
	v_pk_mul_f32 v[14:15], v[30:31], v[14:15]
	v_pk_add_f32 v[22:23], v[68:69], 1.0 op_sel_hi:[1,0]
	v_pk_fma_f32 v[10:11], v[24:25], v[10:11], v[66:67]
	v_pk_fma_f32 v[14:15], v[22:23], v[14:15], v[70:71]
	v_and_b32_sdwa v23, v11, v86 dst_sel:DWORD dst_unused:UNUSED_PAD src0_sel:WORD_1 src1_sel:DWORD
	v_and_b32_sdwa v24, v10, v86 dst_sel:DWORD dst_unused:UNUSED_PAD src0_sel:WORD_1 src1_sel:DWORD
	v_and_b32_sdwa v13, v15, v86 dst_sel:DWORD dst_unused:UNUSED_PAD src0_sel:WORD_1 src1_sel:DWORD
	v_and_b32_sdwa v22, v14, v86 dst_sel:DWORD dst_unused:UNUSED_PAD src0_sel:WORD_1 src1_sel:DWORD
	v_add3_u32 v11, v11, v23, s21
	v_add3_u32 v10, v10, v24, s21
	v_add3_u32 v14, v14, v22, s21
	v_add3_u32 v13, v15, v13, s21
	v_and_b32_e32 v11, 0xffff0000, v11
	v_and_b32_e32 v10, 0xffff0000, v10
	v_or_b32_sdwa v11, v11, v13 dst_sel:DWORD dst_unused:UNUSED_PAD src0_sel:DWORD src1_sel:WORD_1
	v_or_b32_sdwa v10, v10, v14 dst_sel:DWORD dst_unused:UNUSED_PAD src0_sel:DWORD src1_sel:WORD_1
	v_mov_b32_e32 v250, v8
	v_mov_b32_e32 v251, v9
	v_mov_b32_e32 v252, v10
	v_mov_b32_e32 v253, v11
	v_lshl_add_u64 v[14:15], v[16:17], 0, v[56:57]
	global_load_dwordx4 v[8:11], v[42:43], off
	global_load_dwordx4 v[22:25], v[14:15], off
	v_lshl_add_u64 v[14:15], v[18:19], 0, v[56:57]
	global_load_dwordx4 v[26:29], v[14:15], off
	global_store_dwordx2 v[250:251], v[252:253], off
	v_mov_b32_e32 v15, v6
	v_mov_b32_e32 v6, v5
	v_mov_b32_e32 v14, v4
	v_pk_mul_f32 v[6:7], v[6:7], v[12:13] op_sel_hi:[1,0]
	v_or_b32_e32 v4, v87, v81
	v_pk_mul_f32 v[14:15], v[14:15], v[12:13] op_sel_hi:[1,0]
	v_ashrrev_i32_e32 v5, 31, v4
	v_lshlrev_b64 v[4:5], 14, v[4:5]
	v_lshl_add_u64 v[4:5], s[62:63], 0, v[4:5]
	v_lshl_add_u64 v[4:5], v[4:5], 0, v[34:35]
	v_lshl_add_u64 v[4:5], v[4:5], 0, v[20:21]
	s_waitcnt vmcnt(3)
	v_mov_b32_e32 v31, v10
	s_waitcnt vmcnt(2)
	v_mov_b32_e32 v65, v24
	v_mov_b32_e32 v10, v9
	v_mov_b32_e32 v24, v23
	v_mov_b32_e32 v30, v8
	v_mov_b32_e32 v64, v22
	s_waitcnt vmcnt(1)
	v_mov_b32_e32 v67, v28
	v_mov_b32_e32 v28, v27
	v_pk_mul_f32 v[6:7], v[6:7], v[10:11]
	v_pk_add_f32 v[10:11], v[24:25], 1.0 op_sel_hi:[1,0]
	v_mov_b32_e32 v66, v26
	v_pk_mul_f32 v[8:9], v[14:15], v[30:31]
	v_pk_add_f32 v[14:15], v[64:65], 1.0 op_sel_hi:[1,0]
	v_pk_fma_f32 v[6:7], v[6:7], v[10:11], v[28:29]
	v_pk_fma_f32 v[8:9], v[8:9], v[14:15], v[66:67]
	v_and_b32_sdwa v13, v7, v86 dst_sel:DWORD dst_unused:UNUSED_PAD src0_sel:WORD_1 src1_sel:DWORD
	v_and_b32_sdwa v14, v6, v86 dst_sel:DWORD dst_unused:UNUSED_PAD src0_sel:WORD_1 src1_sel:DWORD
	v_and_b32_sdwa v10, v9, v86 dst_sel:DWORD dst_unused:UNUSED_PAD src0_sel:WORD_1 src1_sel:DWORD
	v_and_b32_sdwa v11, v8, v86 dst_sel:DWORD dst_unused:UNUSED_PAD src0_sel:WORD_1 src1_sel:DWORD
	v_add3_u32 v7, v7, v13, s21
	v_add3_u32 v6, v6, v14, s21
	v_add3_u32 v8, v8, v11, s21
	v_add3_u32 v9, v9, v10, s21
	v_and_b32_e32 v7, 0xffff0000, v7
	v_and_b32_e32 v6, 0xffff0000, v6
	v_or_b32_sdwa v7, v7, v9 dst_sel:DWORD dst_unused:UNUSED_PAD src0_sel:DWORD src1_sel:WORD_1
	v_or_b32_sdwa v6, v6, v8 dst_sel:DWORD dst_unused:UNUSED_PAD src0_sel:DWORD src1_sel:WORD_1
	v_mov_b32_e32 v250, v4
	v_mov_b32_e32 v251, v5
	v_mov_b32_e32 v252, v6
	v_mov_b32_e32 v253, v7
	v_lshl_add_u64 v[8:9], v[16:17], 0, v[60:61]
	global_load_dwordx4 v[4:7], v[44:45], off
	v_lshl_add_u64 v[14:15], v[18:19], 0, v[60:61]
	global_load_dwordx4 v[8:11], v[8:9], off
	v_mov_b32_e32 v18, v0
	global_load_dwordx4 v[14:17], v[14:15], off
	global_store_dwordx2 v[250:251], v[252:253], off
	v_or_b32_e32 v0, v87, v82
	v_mov_b32_e32 v19, v2
	v_mov_b32_e32 v2, v1
	v_ashrrev_i32_e32 v1, 31, v0
	v_lshlrev_b64 v[0:1], 14, v[0:1]
	v_lshl_add_u64 v[0:1], s[62:63], 0, v[0:1]
	v_lshl_add_u64 v[0:1], v[0:1], 0, v[34:35]
	v_lshl_add_u64 v[0:1], v[0:1], 0, v[20:21]
	v_pk_mul_f32 v[18:19], v[18:19], v[12:13] op_sel_hi:[1,0]
	v_pk_mul_f32 v[2:3], v[2:3], v[12:13] op_sel_hi:[1,0]
	s_waitcnt vmcnt(3)
	v_mov_b32_e32 v13, v6
	v_mov_b32_e32 v6, v5
	s_waitcnt vmcnt(2)
	v_mov_b32_e32 v21, v10
	v_mov_b32_e32 v10, v9
	v_mov_b32_e32 v12, v4
	v_mov_b32_e32 v20, v8
	s_waitcnt vmcnt(1)
	v_mov_b32_e32 v23, v16
	v_mov_b32_e32 v16, v15
	v_pk_mul_f32 v[2:3], v[2:3], v[6:7]
	v_pk_add_f32 v[6:7], v[10:11], 1.0 op_sel_hi:[1,0]
	v_mov_b32_e32 v22, v14
	v_pk_mul_f32 v[4:5], v[18:19], v[12:13]
	v_pk_add_f32 v[8:9], v[20:21], 1.0 op_sel_hi:[1,0]
	v_pk_fma_f32 v[2:3], v[2:3], v[6:7], v[16:17]
	v_pk_fma_f32 v[4:5], v[4:5], v[8:9], v[22:23]
	v_and_b32_sdwa v8, v3, v86 dst_sel:DWORD dst_unused:UNUSED_PAD src0_sel:WORD_1 src1_sel:DWORD
	v_and_b32_sdwa v9, v2, v86 dst_sel:DWORD dst_unused:UNUSED_PAD src0_sel:WORD_1 src1_sel:DWORD
	v_and_b32_sdwa v6, v5, v86 dst_sel:DWORD dst_unused:UNUSED_PAD src0_sel:WORD_1 src1_sel:DWORD
	v_and_b32_sdwa v7, v4, v86 dst_sel:DWORD dst_unused:UNUSED_PAD src0_sel:WORD_1 src1_sel:DWORD
	v_add3_u32 v3, v3, v8, s21
	v_add3_u32 v2, v2, v9, s21
	v_add3_u32 v4, v4, v7, s21
	v_add3_u32 v5, v5, v6, s21
	v_and_b32_e32 v3, 0xffff0000, v3
	v_and_b32_e32 v2, 0xffff0000, v2
	v_or_b32_sdwa v3, v3, v5 dst_sel:DWORD dst_unused:UNUSED_PAD src0_sel:DWORD src1_sel:WORD_1
	v_or_b32_sdwa v2, v2, v4 dst_sel:DWORD dst_unused:UNUSED_PAD src0_sel:DWORD src1_sel:WORD_1
	global_store_dwordx2 v[0:1], v[2:3], off
	s_branch .LBB0_1936

; template <int MODE>
; __device__ __forceinline__ void norm_phase(const Params& p, const float* src, const float* w, const float* modl, int sh_off, int sc_off,
;                            char* smem, int bid, int nblk) {
;     ...
;   auto process = [&](int row, f32x4 (&v)[4]) {
;     float ss = 0.f;
; #pragma unroll
;     for (int i = 0; i < 4; ++i) ss += v[i][0] * v[i][0] + v[i][1] * v[i][1] + v[i][2] * v[i][2] + v[i][3] * v[i][3];
; #pragma unroll
;     for (int o = 32; o >= 1; o >>= 1) ss += __shfl_xor(ss, o);
;     const float rstd = rsqrtf(ss * (1.f / 1024.f) + 1e-6f);
;     const int b = row >> 13;
;     float dots[8];
;     if (MODE == 1) { for (int j = 0; j < 8; ++j) dots[j] = 0.f; }
; #pragma unroll
;     for (int i = 0; i < 4; ++i) {
;       const int c0 = i * 256 + lane * 4;
;       f32x4 ww = *(const f32x4*)(w + c0);
;       f32x4 y;
;       if (MODE == 2) {
; #pragma unroll
;         for (int e = 0; e < 4; ++e) y[e] = v[i][e] * rstd * ww[e];
;         *(f32x4*)(p.out + (size_t)row * 1024 + c0) = y;
;     ...
;   for (int row = bid * 4 + wid; row < M; row += nblk * 8) {
;     const int row1 = row + nblk * 4;
;     const bool has1 = row1 < M;
;     f32x4 v0[4], v1[4];
; #pragma unroll
;     for (int i = 0; i < 4; ++i) v0[i] = *(const f32x4*)(src + (size_t)row * 1024 + i * 256 + lane * 4);
; #pragma unroll
;     for (int i = 0; i < 4; ++i) v1[i] = has1 ? *(const f32x4*)(src + (size_t)row1 * 1024 + i * 256 + lane * 4) : f32x4{0.f, 0.f, 0.f, 0.f};
;     process(row, v0);
;     if (has1) process(row1, v1);
.LBB0_2163:
	s_or_b64 exec, exec, s[0:1]
	global_load_dwordx4 v[50:53], v[34:35], off
	s_waitcnt vmcnt(0)
	v_pk_mul_f32 v[58:59], v[28:29], v[28:29]
	v_pk_mul_f32 v[60:61], v[24:25], v[24:25]
	v_pk_mul_f32 v[54:55], v[30:31], v[30:31]
	v_pk_mul_f32 v[56:57], v[26:27], v[26:27]
	v_mov_b32_e32 v64, v17
	v_mov_b32_e32 v65, v21
	v_mov_b32_e32 v70, v58
	v_mov_b32_e32 v71, v60
	v_mov_b32_e32 v60, v59
	v_mov_b32_e32 v62, v16
	v_mov_b32_e32 v63, v20
	v_mov_b32_e32 v58, v54
	v_mov_b32_e32 v59, v56
	v_mov_b32_e32 v56, v55
	v_pk_mul_f32 v[54:55], v[64:65], v[64:65]
	v_pk_add_f32 v[60:61], v[70:71], v[60:61]
	v_mov_b32_e32 v66, v18
	v_mov_b32_e32 v67, v22
	v_pk_fma_f32 v[54:55], v[62:63], v[62:63], v[54:55]
	v_pk_add_f32 v[58:59], v[58:59], v[60:61]
	v_mov_b32_e32 v68, v19
	v_mov_b32_e32 v69, v23
	v_pk_fma_f32 v[54:55], v[66:67], v[66:67], v[54:55]
	v_pk_add_f32 v[56:57], v[56:57], v[58:59]
	v_pk_fma_f32 v[54:55], v[68:69], v[68:69], v[54:55]
	v_add_f32_e32 v37, v56, v57
	v_add_f32_e32 v37, v55, v37
	v_add_f32_e32 v37, v54, v37
	s_nop 1
	v_mov_b32_e32 v49, v37
	s_nop 1
	v_permlane32_swap_b32_e32 v37, v49
	s_waitcnt lgkmcnt(0)
	v_add_f32_e32 v37, v37, v49
	s_nop 1
	v_mov_b32_e32 v49, v37
	s_nop 1
	v_permlane16_swap_b32_e32 v37, v49
	s_waitcnt lgkmcnt(0)
	v_add_f32_e32 v37, v37, v49
	s_nop 1
	v_mov_b32_dpp v49, v37 row_ror:8 row_mask:0xf bank_mask:0xf
	s_waitcnt lgkmcnt(0)
	v_add_f32_e32 v37, v37, v49
	s_nop 1
	v_mov_b32_dpp v49, v37 row_ror:4 row_mask:0xf bank_mask:0xf
	s_waitcnt lgkmcnt(0)
	v_add_f32_e32 v37, v37, v49
	s_nop 1
	v_mov_b32_dpp v49, v37 quad_perm:[2,3,0,1] row_mask:0xf bank_mask:0xf
	s_waitcnt lgkmcnt(0)
	v_add_f32_e32 v37, v37, v49
	s_nop 1
	v_mov_b32_dpp v49, v37 quad_perm:[1,0,3,2] row_mask:0xf bank_mask:0xf
	s_waitcnt lgkmcnt(0)
	v_add_f32_e32 v37, v37, v49
	v_fmamk_f32 v37, v37, 0x3a800000, v48
	v_mul_f32_e32 v49, 0x4b800000, v37
	v_cmp_gt_f32_e64 s[0:1], s8, v37
	s_nop 1
	v_cndmask_b32_e64 v37, v37, v49, s[0:1]
	v_rsq_f32_e32 v37, v37
	s_nop 0
	v_mul_f32_e32 v49, 0x45800000, v37
	v_cndmask_b32_e64 v54, v37, v49, s[0:1]
	v_pk_mul_f32 v[28:29], v[28:29], v[54:55] op_sel_hi:[1,0]
	v_pk_mul_f32 v[30:31], v[30:31], v[54:55] op_sel_hi:[1,0]
	v_pk_mul_f32 v[24:25], v[24:25], v[54:55] op_sel_hi:[1,0]
	v_pk_mul_f32 v[28:29], v[50:51], v[28:29]
	v_pk_mul_f32 v[30:31], v[52:53], v[30:31]
	global_store_dwordx4 v[40:41], v[28:31], off
	global_load_dwordx4 v[28:31], v[34:35], off offset:1024
	v_pk_mul_f32 v[26:27], v[26:27], v[54:55] op_sel_hi:[1,0]
	v_pk_mul_f32 v[20:21], v[20:21], v[54:55] op_sel_hi:[1,0]
	v_pk_mul_f32 v[22:23], v[22:23], v[54:55] op_sel_hi:[1,0]
	v_pk_mul_f32 v[16:17], v[16:17], v[54:55] op_sel_hi:[1,0]
	v_pk_mul_f32 v[18:19], v[18:19], v[54:55] op_sel_hi:[1,0]
	s_waitcnt vmcnt(0)
	v_pk_mul_f32 v[24:25], v[28:29], v[24:25]
	v_pk_mul_f32 v[26:27], v[30:31], v[26:27]
	global_store_dwordx4 v[40:41], v[24:27], off offset:1024
	global_load_dwordx4 v[24:27], v[34:35], off offset:2048
	s_waitcnt vmcnt(0)
	v_pk_mul_f32 v[20:21], v[24:25], v[20:21]
	v_pk_mul_f32 v[22:23], v[26:27], v[22:23]
	global_store_dwordx4 v[40:41], v[20:23], off offset:2048
	global_load_dwordx4 v[20:23], v[34:35], off offset:3072
	s_waitcnt vmcnt(0)
	v_pk_mul_f32 v[16:17], v[20:21], v[16:17]
	v_pk_mul_f32 v[18:19], v[22:23], v[18:19]
	global_store_dwordx4 v[40:41], v[16:19], off offset:3072
	s_and_saveexec_b64 s[0:1], vcc
	s_cbranch_execz .LBB0_2154
	global_load_dwordx4 v[16:19], v[34:35], off
	v_pk_mul_f32 v[24:25], v[8:9], v[8:9]
	v_pk_mul_f32 v[26:27], v[4:5], v[4:5]
	v_pk_mul_f32 v[20:21], v[6:7], v[6:7]
	v_pk_mul_f32 v[22:23], v[10:11], v[10:11]
	v_mov_b32_e32 v30, v1
	v_mov_b32_e32 v31, v13
	v_mov_b32_e32 v52, v26
	v_mov_b32_e32 v53, v24
	v_mov_b32_e32 v24, v27
	v_mov_b32_e32 v28, v0
	v_mov_b32_e32 v29, v12
	v_mov_b32_e32 v26, v20
	v_mov_b32_e32 v27, v22
	v_mov_b32_e32 v22, v21
	v_pk_mul_f32 v[20:21], v[30:31], v[30:31]
	v_pk_add_f32 v[24:25], v[52:53], v[24:25]
	v_mov_b32_e32 v40, v2
	v_mov_b32_e32 v41, v14
	v_pk_fma_f32 v[20:21], v[28:29], v[28:29], v[20:21]
	v_pk_add_f32 v[24:25], v[26:27], v[24:25]
	v_mov_b32_e32 v50, v3
	v_mov_b32_e32 v51, v15
	v_pk_fma_f32 v[20:21], v[40:41], v[40:41], v[20:21]
	v_pk_add_f32 v[22:23], v[22:23], v[24:25]
	v_pk_fma_f32 v[20:21], v[50:51], v[50:51], v[20:21]
	v_add_f32_e32 v22, v22, v23
	v_add_f32_e32 v20, v20, v22
	v_add_f32_e32 v20, v20, v21
	s_nop 1
	v_mov_b32_e32 v21, v20
	s_nop 1
	v_permlane32_swap_b32_e32 v20, v21
	s_waitcnt lgkmcnt(0)
	v_add_f32_e32 v20, v20, v21
	s_nop 1
	v_mov_b32_e32 v21, v20
	s_nop 1
	v_permlane16_swap_b32_e32 v20, v21
	s_waitcnt lgkmcnt(0)
	v_add_f32_e32 v20, v20, v21
	s_nop 1
	v_mov_b32_dpp v21, v20 row_ror:8 row_mask:0xf bank_mask:0xf
	s_waitcnt lgkmcnt(0)
	v_add_f32_e32 v20, v20, v21
	s_nop 1
	v_mov_b32_dpp v21, v20 row_ror:4 row_mask:0xf bank_mask:0xf
	s_waitcnt lgkmcnt(0)
	v_add_f32_e32 v20, v20, v21
	s_nop 1
	v_mov_b32_dpp v21, v20 quad_perm:[2,3,0,1] row_mask:0xf bank_mask:0xf
	s_waitcnt lgkmcnt(0)
	v_add_f32_e32 v20, v20, v21
	s_nop 1
	v_mov_b32_dpp v21, v20 quad_perm:[1,0,3,2] row_mask:0xf bank_mask:0xf
	s_waitcnt lgkmcnt(0)
	v_add_f32_e32 v20, v20, v21
	v_fmamk_f32 v20, v20, 0x3a800000, v48
	v_mul_f32_e32 v21, 0x4b800000, v20
	v_cmp_gt_f32_e32 vcc, s8, v20
	s_nop 1
	v_cndmask_b32_e32 v20, v20, v21, vcc
	v_rsq_f32_e32 v20, v20
	s_nop 0
	v_mul_f32_e32 v21, 0x45800000, v20
	v_cndmask_b32_e32 v20, v20, v21, vcc
	v_pk_mul_f32 v[4:5], v[4:5], v[20:21] op_sel_hi:[1,0]
	v_pk_mul_f32 v[6:7], v[6:7], v[20:21] op_sel_hi:[1,0]
	v_pk_mul_f32 v[8:9], v[8:9], v[20:21] op_sel_hi:[1,0]
	s_waitcnt vmcnt(0)
	v_pk_mul_f32 v[4:5], v[16:17], v[4:5]
	v_pk_mul_f32 v[6:7], v[18:19], v[6:7]
	global_store_dwordx4 v[38:39], v[4:7], off
	global_load_dwordx4 v[4:7], v[34:35], off offset:1024
	v_pk_mul_f32 v[10:11], v[10:11], v[20:21] op_sel_hi:[1,0]
	v_pk_mul_f32 v[0:1], v[0:1], v[20:21] op_sel_hi:[1,0]
	v_pk_mul_f32 v[2:3], v[2:3], v[20:21] op_sel_hi:[1,0]
	s_waitcnt vmcnt(0)
	v_pk_mul_f32 v[4:5], v[4:5], v[8:9]
	v_pk_mul_f32 v[6:7], v[6:7], v[10:11]
	global_store_dwordx4 v[38:39], v[4:7], off offset:1024
	global_load_dwordx4 v[4:7], v[34:35], off offset:2048
	s_waitcnt vmcnt(0)
	v_pk_mul_f32 v[0:1], v[4:5], v[0:1]
	v_pk_mul_f32 v[2:3], v[6:7], v[2:3]
	global_store_dwordx4 v[38:39], v[0:3], off offset:2048
	global_load_dwordx4 v[0:3], v[34:35], off offset:3072
	v_pk_mul_f32 v[4:5], v[12:13], v[20:21] op_sel_hi:[1,0]
	v_pk_mul_f32 v[6:7], v[14:15], v[20:21] op_sel_hi:[1,0]
	s_waitcnt vmcnt(0)
	v_pk_mul_f32 v[0:1], v[0:1], v[4:5]
	v_pk_mul_f32 v[2:3], v[2:3], v[6:7]
	global_store_dwordx4 v[38:39], v[0:3], off offset:3072
	s_branch .LBB0_2154
